# RWKV scanner: counted lgkmcnt at chunk start (first step no longer waits for all nine operand loads)
# speedup vs baseline: 1.0018x; 1.0018x over previous
; template <int CPL>
; DI void scan_block2(CP p, int layer, int s, int d, int hd, int rowhalf, char* smem) {
;     ...
;       const float* ob = OP + (c & 1) * 32 * 392;
;       float* yb = YB + (c & 1) * 2048;
;       float* ydst = cg == 0 ? yb + row : (float*)(smem + 147712) + lane;
;       const int ystride = cg == 0 ? 64 : 0;
;       float4 ca[CPL / 4], cy[CPL / 4], cw[CPL / 4], cb[CPL / 4], ck[CPL / 4];
;       float cvv;
;       {
;         const float* o = ob + cg * CPL;
; #pragma unroll
;         for (int i = 0; i < CPL / 4; ++i) {
;           ca[i] = *(const float4*)(o + 4 * i); cy[i] = *(const float4*)(o + 64 + 4 * i); cw[i] = *(const float4*)(o + 128 + 4 * i);
;           cb[i] = *(const float4*)(o + 192 + 4 * i); ck[i] = *(const float4*)(o + 256 + 4 * i);
;         }
;         cvv = ob[320 + row];
;     ...
;         f2 pa0 = S[0] * A[0], pa1 = S[1] * A[1];
; #pragma unroll
;         for (int i = 2; i < NV; i += 2) { pa0 = S[i] * A[i] + pa0; pa1 = S[i + 1] * A[i + 1] + pa1; }
;         pa0 = pa0 + pa1;
;         float da = pa0.x + pa0.y;
;         const f2 vvv = mk2(vv, vv);
;         f2 SW[NV];
; #pragma unroll
;         for (int i = 0; i < NV; ++i) SW[i] = S[i] * W[i] + vvv * K[i];
;         da += __int_as_float(__builtin_amdgcn_update_dpp(0, __float_as_int(da), 0xB1, 0xf, 0xf, false));
;         da += __int_as_float(__builtin_amdgcn_update_dpp(0, __float_as_int(da), 0x4E, 0xf, 0xf, false));
;         if (CPL == 8) da += __int_as_float(__builtin_amdgcn_update_dpp(0, __float_as_int(da), 0x141, 0xf, 0xf, false));
;         const f2 dav = mk2(da, da);
; #pragma unroll
;         for (int i = 0; i < NV; ++i) S[i] = dav * B[i] + SW[i];
;         f2 py0 = S[0] * Y[0], py1 = S[1] * Y[1];
; #pragma unroll
;         for (int i = 2; i < NV; i += 2) { py0 = S[i] * Y[i] + py0; py1 = S[i + 1] * Y[i + 1] + py1; }
;         py0 = py0 + py1;
;         float yv = py0.x + py0.y;
;         yv += __int_as_float(__builtin_amdgcn_update_dpp(0, __float_as_int(yv), 0xB1, 0xf, 0xf, false));
;         yv += __int_as_float(__builtin_amdgcn_update_dpp(0, __float_as_int(yv), 0x4E, 0xf, 0xf, false));
;         if (CPL == 8) yv += __int_as_float(__builtin_amdgcn_update_dpp(0, __float_as_int(yv), 0x141, 0xf, 0xf, false));
;         ydst[jj * ystride] = yv;
.Lsc8_chunk:
	s_and_b32 s17, s10, 1
	s_mul_i32 s15, s17, 0xc400
	v_add_u32_e32 v199, s15, v202
	v_add_u32_e32 v200, s15, v205
	s_lshl_b32 s15, s17, 13
	v_add_u32_e32 v0, s15, v204
	v_cndmask_b32_e32 v201, v206, v0, vcc
	ds_read_b128 v[2:5], v199 offset:0
	ds_read_b128 v[6:9], v199 offset:16
	ds_read_b128 v[34:37], v199 offset:1024
	ds_read_b128 v[38:41], v199 offset:1040
	ds_read_b32 v42, v200 offset:0
	ds_read_b128 v[26:29], v199 offset:768
	ds_read_b128 v[30:33], v199 offset:784
	ds_read_b128 v[10:13], v199 offset:256
	ds_read_b128 v[14:17], v199 offset:272
	s_waitcnt lgkmcnt(7)
	v_pk_mul_f32 v[88:89], v[2:3], v[170:171]
	ds_read_b128 v[44:47], v199 offset:1568
	v_pk_fma_f32 v[88:89], v[4:5], v[172:173], v[88:89]
	ds_read_b128 v[48:51], v199 offset:1584
	v_pk_fma_f32 v[88:89], v[6:7], v[174:175], v[88:89]
	ds_read_b128 v[76:79], v199 offset:2592
	v_pk_fma_f32 v[88:89], v[8:9], v[176:177], v[88:89]
	ds_read_b128 v[80:83], v199 offset:2608
	v_add_f32_e32 v86, v88, v89
	ds_read_b32 v84, v200 offset:1568
	s_waitcnt lgkmcnt(9)
	v_pk_fma_f32 v[162:163], v[34:35], v[42:43], v[170:171] op_sel_hi:[1,0,1]
	v_add_f32_dpp v86, v86, v86 quad_perm:[1,0,3,2] row_mask:0xf bank_mask:0xf bound_ctrl:1
	v_pk_fma_f32 v[164:165], v[36:37], v[42:43], v[172:173] op_sel_hi:[1,0,1]
	ds_read_b128 v[68:71], v199 offset:2336
	v_add_f32_dpp v86, v86, v86 quad_perm:[2,3,0,1] row_mask:0xf bank_mask:0xf bound_ctrl:1
	s_nop 0
	ds_read_b128 v[72:75], v199 offset:2352
	v_add_f32_dpp v86, v86, v86 row_half_mirror row_mask:0xf bank_mask:0xf bound_ctrl:1
	v_pk_fma_f32 v[166:167], v[38:39], v[42:43], v[174:175] op_sel_hi:[1,0,1]
	v_pk_fma_f32 v[168:169], v[40:41], v[42:43], v[176:177] op_sel_hi:[1,0,1]
	s_waitcnt lgkmcnt(9)
	v_pk_fma_f32 v[94:95], v[26:27], v[86:87], v[162:163] op_sel_hi:[1,0,1]
	v_pk_fma_f32 v[96:97], v[28:29], v[86:87], v[164:165] op_sel_hi:[1,0,1]
	v_pk_fma_f32 v[98:99], v[30:31], v[86:87], v[166:167] op_sel_hi:[1,0,1]
	v_pk_fma_f32 v[100:101], v[32:33], v[86:87], v[168:169] op_sel_hi:[1,0,1]
	ds_read_b128 v[52:55], v199 offset:1824
	ds_read_b128 v[56:59], v199 offset:1840
	s_waitcnt lgkmcnt(4)
	v_pk_mul_f32 v[88:89], v[44:45], v[94:95]
	ds_read_b128 v[2:5], v199 offset:3136
	v_pk_fma_f32 v[88:89], v[46:47], v[96:97], v[88:89]
	ds_read_b128 v[6:9], v199 offset:3152
	v_pk_fma_f32 v[88:89], v[48:49], v[98:99], v[88:89]
	ds_read_b128 v[34:37], v199 offset:4160
	v_pk_fma_f32 v[88:89], v[50:51], v[100:101], v[88:89]
	ds_read_b128 v[38:41], v199 offset:4176
	v_add_f32_e32 v86, v88, v89
	ds_read_b32 v42, v200 offset:3136
	v_pk_fma_f32 v[162:163], v[76:77], v[84:85], v[94:95] op_sel_hi:[1,0,1]
	v_add_f32_dpp v86, v86, v86 quad_perm:[1,0,3,2] row_mask:0xf bank_mask:0xf bound_ctrl:1
	v_pk_fma_f32 v[164:165], v[78:79], v[84:85], v[96:97] op_sel_hi:[1,0,1]
	ds_read_b128 v[26:29], v199 offset:3904
	v_add_f32_dpp v86, v86, v86 quad_perm:[2,3,0,1] row_mask:0xf bank_mask:0xf bound_ctrl:1
	s_nop 0
	ds_read_b128 v[30:33], v199 offset:3920
	v_add_f32_dpp v86, v86, v86 row_half_mirror row_mask:0xf bank_mask:0xf bound_ctrl:1
	v_pk_fma_f32 v[166:167], v[80:81], v[84:85], v[98:99] op_sel_hi:[1,0,1]
	v_pk_fma_f32 v[168:169], v[82:83], v[84:85], v[100:101] op_sel_hi:[1,0,1]
	s_waitcnt lgkmcnt(9)
	v_pk_fma_f32 v[170:171], v[68:69], v[86:87], v[162:163] op_sel_hi:[1,0,1]
	v_pk_fma_f32 v[172:173], v[70:71], v[86:87], v[164:165] op_sel_hi:[1,0,1]
	v_pk_fma_f32 v[174:175], v[72:73], v[86:87], v[166:167] op_sel_hi:[1,0,1]
	v_pk_fma_f32 v[176:177], v[74:75], v[86:87], v[168:169] op_sel_hi:[1,0,1]
	v_pk_mul_f32 v[90:91], v[10:11], v[94:95]
	v_pk_fma_f32 v[90:91], v[12:13], v[96:97], v[90:91]
	v_pk_fma_f32 v[90:91], v[14:15], v[98:99], v[90:91]
	v_pk_fma_f32 v[90:91], v[16:17], v[100:101], v[90:91]
	ds_read_b128 v[10:13], v199 offset:3392
	v_add_f32_e32 v92, v90, v91
	ds_read_b128 v[14:17], v199 offset:3408
	s_waitcnt lgkmcnt(4)
	v_pk_mul_f32 v[88:89], v[2:3], v[170:171]
	ds_read_b128 v[44:47], v199 offset:4704
	v_pk_fma_f32 v[88:89], v[4:5], v[172:173], v[88:89]
	ds_read_b128 v[48:51], v199 offset:4720
	v_pk_fma_f32 v[88:89], v[6:7], v[174:175], v[88:89]
	ds_read_b128 v[76:79], v199 offset:5728
	v_pk_fma_f32 v[88:89], v[8:9], v[176:177], v[88:89]
	ds_read_b128 v[80:83], v199 offset:5744
	v_add_f32_e32 v86, v88, v89
	ds_read_b32 v84, v200 offset:4704
	v_pk_fma_f32 v[162:163], v[34:35], v[42:43], v[170:171] op_sel_hi:[1,0,1]
	v_add_f32_dpp v86, v86, v86 quad_perm:[1,0,3,2] row_mask:0xf bank_mask:0xf bound_ctrl:1
	v_add_f32_dpp v92, v92, v92 quad_perm:[1,0,3,2] row_mask:0xf bank_mask:0xf bound_ctrl:1
	ds_read_b128 v[68:71], v199 offset:5472
	v_add_f32_dpp v86, v86, v86 quad_perm:[2,3,0,1] row_mask:0xf bank_mask:0xf bound_ctrl:1
	v_add_f32_dpp v92, v92, v92 quad_perm:[2,3,0,1] row_mask:0xf bank_mask:0xf bound_ctrl:1
	ds_read_b128 v[72:75], v199 offset:5488
	v_add_f32_dpp v86, v86, v86 row_half_mirror row_mask:0xf bank_mask:0xf bound_ctrl:1
	v_add_f32_dpp v92, v92, v92 row_half_mirror row_mask:0xf bank_mask:0xf bound_ctrl:1
	v_pk_fma_f32 v[164:165], v[36:37], v[42:43], v[172:173] op_sel_hi:[1,0,1]
	v_pk_fma_f32 v[166:167], v[38:39], v[42:43], v[174:175] op_sel_hi:[1,0,1]
	v_pk_fma_f32 v[168:169], v[40:41], v[42:43], v[176:177] op_sel_hi:[1,0,1]
	s_waitcnt lgkmcnt(9)
	v_pk_fma_f32 v[94:95], v[26:27], v[86:87], v[162:163] op_sel_hi:[1,0,1]
	v_pk_fma_f32 v[96:97], v[28:29], v[86:87], v[164:165] op_sel_hi:[1,0,1]
	v_pk_fma_f32 v[98:99], v[30:31], v[86:87], v[166:167] op_sel_hi:[1,0,1]
	v_pk_fma_f32 v[100:101], v[32:33], v[86:87], v[168:169] op_sel_hi:[1,0,1]
	ds_write_b32 v201, v92 offset:0
	v_pk_mul_f32 v[90:91], v[52:53], v[170:171]
	v_pk_fma_f32 v[90:91], v[54:55], v[172:173], v[90:91]
	v_pk_fma_f32 v[90:91], v[56:57], v[174:175], v[90:91]
	v_pk_fma_f32 v[90:91], v[58:59], v[176:177], v[90:91]
	ds_read_b128 v[52:55], v199 offset:4960
	v_add_f32_e32 v93, v90, v91
	ds_read_b128 v[56:59], v199 offset:4976
	s_waitcnt lgkmcnt(5)
; template <int CPL>
; DI void scan_block2(CP p, int layer, int s, int d, int hd, int rowhalf, char* smem) {
;     ...
;       for (int jj = 0; jj < nst; ++jj) {
;         float4 na[CPL / 4], ny[CPL / 4], nw[CPL / 4], nb[CPL / 4], nk[CPL / 4];
;         float nvv;
;         {
;           const int jn = jj + 1;
;           const float* o = ob + jn * 392 + cg * CPL;
; #pragma unroll
;           for (int i = 0; i < CPL / 4; ++i) {
;             na[i] = *(const float4*)(o + 4 * i); ny[i] = *(const float4*)(o + 64 + 4 * i); nw[i] = *(const float4*)(o + 128 + 4 * i);
;             nb[i] = *(const float4*)(o + 192 + 4 * i); nk[i] = *(const float4*)(o + 256 + 4 * i);
;           }
;           nvv = ob[jn * 392 + 320 + row];
;         }
;         f2 A[NV], Y[NV], W[NV], B[NV], K[NV];
; #pragma unroll
;         for (int i = 0; i < CPL / 4; ++i) {
;           A[2 * i] = mk2(ca[i].x, ca[i].y); A[2 * i + 1] = mk2(ca[i].z, ca[i].w);
;           Y[2 * i] = mk2(cy[i].x, cy[i].y); Y[2 * i + 1] = mk2(cy[i].z, cy[i].w);
;           W[2 * i] = mk2(cw[i].x, cw[i].y); W[2 * i + 1] = mk2(cw[i].z, cw[i].w);
;           B[2 * i] = mk2(cb[i].x, cb[i].y); B[2 * i + 1] = mk2(cb[i].z, cb[i].w);
;           K[2 * i] = mk2(ck[i].x, ck[i].y); K[2 * i + 1] = mk2(ck[i].z, ck[i].w);
;         }
;         const float vv = cvv;
;         f2 pa0 = S[0] * A[0], pa1 = S[1] * A[1];
; #pragma unroll
;         for (int i = 2; i < NV; i += 2) { pa0 = S[i] * A[i] + pa0; pa1 = S[i + 1] * A[i + 1] + pa1; }
;         pa0 = pa0 + pa1;
;         float da = pa0.x + pa0.y;
;         const f2 vvv = mk2(vv, vv);
;         f2 SW[NV];
; #pragma unroll
;         for (int i = 0; i < NV; ++i) SW[i] = S[i] * W[i] + vvv * K[i];
;         da += __int_as_float(__builtin_amdgcn_update_dpp(0, __float_as_int(da), 0xB1, 0xf, 0xf, false));
;         da += __int_as_float(__builtin_amdgcn_update_dpp(0, __float_as_int(da), 0x4E, 0xf, 0xf, false));
;         if (CPL == 8) da += __int_as_float(__builtin_amdgcn_update_dpp(0, __float_as_int(da), 0x141, 0xf, 0xf, false));
;         const f2 dav = mk2(da, da);
; #pragma unroll
;         for (int i = 0; i < NV; ++i) S[i] = dav * B[i] + SW[i];
;         f2 py0 = S[0] * Y[0], py1 = S[1] * Y[1];
; #pragma unroll
;         for (int i = 2; i < NV; i += 2) { py0 = S[i] * Y[i] + py0; py1 = S[i + 1] * Y[i + 1] + py1; }
;         py0 = py0 + py1;
;         float yv = py0.x + py0.y;
	v_pk_mul_f32 v[88:89], v[44:45], v[94:95]
	ds_read_b128 v[2:5], v199 offset:6272
	v_pk_fma_f32 v[88:89], v[46:47], v[96:97], v[88:89]
	ds_read_b128 v[6:9], v199 offset:6288
	v_pk_fma_f32 v[88:89], v[48:49], v[98:99], v[88:89]
	ds_read_b128 v[34:37], v199 offset:7296
	v_pk_fma_f32 v[88:89], v[50:51], v[100:101], v[88:89]
	ds_read_b128 v[38:41], v199 offset:7312
	v_add_f32_e32 v86, v88, v89
	ds_read_b32 v42, v200 offset:6272
	v_pk_fma_f32 v[162:163], v[76:77], v[84:85], v[94:95] op_sel_hi:[1,0,1]
	v_add_f32_dpp v86, v86, v86 quad_perm:[1,0,3,2] row_mask:0xf bank_mask:0xf bound_ctrl:1
	v_add_f32_dpp v93, v93, v93 quad_perm:[1,0,3,2] row_mask:0xf bank_mask:0xf bound_ctrl:1
	ds_read_b128 v[26:29], v199 offset:7040
	v_add_f32_dpp v86, v86, v86 quad_perm:[2,3,0,1] row_mask:0xf bank_mask:0xf bound_ctrl:1
	v_add_f32_dpp v93, v93, v93 quad_perm:[2,3,0,1] row_mask:0xf bank_mask:0xf bound_ctrl:1
	ds_read_b128 v[30:33], v199 offset:7056
	v_add_f32_dpp v86, v86, v86 row_half_mirror row_mask:0xf bank_mask:0xf bound_ctrl:1
	v_add_f32_dpp v93, v93, v93 row_half_mirror row_mask:0xf bank_mask:0xf bound_ctrl:1
	v_pk_fma_f32 v[164:165], v[78:79], v[84:85], v[96:97] op_sel_hi:[1,0,1]
	v_pk_fma_f32 v[166:167], v[80:81], v[84:85], v[98:99] op_sel_hi:[1,0,1]
	v_pk_fma_f32 v[168:169], v[82:83], v[84:85], v[100:101] op_sel_hi:[1,0,1]
	s_waitcnt lgkmcnt(10)
	v_pk_fma_f32 v[170:171], v[68:69], v[86:87], v[162:163] op_sel_hi:[1,0,1]
	v_pk_fma_f32 v[172:173], v[70:71], v[86:87], v[164:165] op_sel_hi:[1,0,1]
	v_pk_fma_f32 v[174:175], v[72:73], v[86:87], v[166:167] op_sel_hi:[1,0,1]
	v_pk_fma_f32 v[176:177], v[74:75], v[86:87], v[168:169] op_sel_hi:[1,0,1]
	ds_write_b32 v201, v93 offset:256
	v_pk_mul_f32 v[90:91], v[10:11], v[94:95]
	v_pk_fma_f32 v[90:91], v[12:13], v[96:97], v[90:91]
	v_pk_fma_f32 v[90:91], v[14:15], v[98:99], v[90:91]
	v_pk_fma_f32 v[90:91], v[16:17], v[100:101], v[90:91]
	ds_read_b128 v[10:13], v199 offset:6528
	v_add_f32_e32 v92, v90, v91
	ds_read_b128 v[14:17], v199 offset:6544
	s_waitcnt lgkmcnt(5)
	v_pk_mul_f32 v[88:89], v[2:3], v[170:171]
	ds_read_b128 v[44:47], v199 offset:7840
	v_pk_fma_f32 v[88:89], v[4:5], v[172:173], v[88:89]
	ds_read_b128 v[48:51], v199 offset:7856
	v_pk_fma_f32 v[88:89], v[6:7], v[174:175], v[88:89]
	ds_read_b128 v[76:79], v199 offset:8864
	v_pk_fma_f32 v[88:89], v[8:9], v[176:177], v[88:89]
	ds_read_b128 v[80:83], v199 offset:8880
	v_add_f32_e32 v86, v88, v89
	ds_read_b32 v84, v200 offset:7840
	v_pk_fma_f32 v[162:163], v[34:35], v[42:43], v[170:171] op_sel_hi:[1,0,1]
	v_add_f32_dpp v86, v86, v86 quad_perm:[1,0,3,2] row_mask:0xf bank_mask:0xf bound_ctrl:1
	v_add_f32_dpp v92, v92, v92 quad_perm:[1,0,3,2] row_mask:0xf bank_mask:0xf bound_ctrl:1
	ds_read_b128 v[68:71], v199 offset:8608
	v_add_f32_dpp v86, v86, v86 quad_perm:[2,3,0,1] row_mask:0xf bank_mask:0xf bound_ctrl:1
	v_add_f32_dpp v92, v92, v92 quad_perm:[2,3,0,1] row_mask:0xf bank_mask:0xf bound_ctrl:1
	ds_read_b128 v[72:75], v199 offset:8624
	v_add_f32_dpp v86, v86, v86 row_half_mirror row_mask:0xf bank_mask:0xf bound_ctrl:1
	v_add_f32_dpp v92, v92, v92 row_half_mirror row_mask:0xf bank_mask:0xf bound_ctrl:1
	v_pk_fma_f32 v[164:165], v[36:37], v[42:43], v[172:173] op_sel_hi:[1,0,1]
	v_pk_fma_f32 v[166:167], v[38:39], v[42:43], v[174:175] op_sel_hi:[1,0,1]
	v_pk_fma_f32 v[168:169], v[40:41], v[42:43], v[176:177] op_sel_hi:[1,0,1]
	s_waitcnt lgkmcnt(10)
	v_pk_fma_f32 v[94:95], v[26:27], v[86:87], v[162:163] op_sel_hi:[1,0,1]
	v_pk_fma_f32 v[96:97], v[28:29], v[86:87], v[164:165] op_sel_hi:[1,0,1]
	v_pk_fma_f32 v[98:99], v[30:31], v[86:87], v[166:167] op_sel_hi:[1,0,1]
	v_pk_fma_f32 v[100:101], v[32:33], v[86:87], v[168:169] op_sel_hi:[1,0,1]
	ds_write_b32 v201, v92 offset:512
	v_pk_mul_f32 v[90:91], v[52:53], v[170:171]
	v_pk_fma_f32 v[90:91], v[54:55], v[172:173], v[90:91]
	v_pk_fma_f32 v[90:91], v[56:57], v[174:175], v[90:91]
	v_pk_fma_f32 v[90:91], v[58:59], v[176:177], v[90:91]
	ds_read_b128 v[52:55], v199 offset:8096
	v_add_f32_e32 v93, v90, v91
	ds_read_b128 v[56:59], v199 offset:8112
	s_waitcnt lgkmcnt(5)
	v_pk_mul_f32 v[88:89], v[44:45], v[94:95]
	ds_read_b128 v[2:5], v199 offset:9408
	v_pk_fma_f32 v[88:89], v[46:47], v[96:97], v[88:89]
	ds_read_b128 v[6:9], v199 offset:9424
	v_pk_fma_f32 v[88:89], v[48:49], v[98:99], v[88:89]
	ds_read_b128 v[34:37], v199 offset:10432
	v_pk_fma_f32 v[88:89], v[50:51], v[100:101], v[88:89]
	ds_read_b128 v[38:41], v199 offset:10448
	v_add_f32_e32 v86, v88, v89
	ds_read_b32 v42, v200 offset:9408
	v_pk_fma_f32 v[162:163], v[76:77], v[84:85], v[94:95] op_sel_hi:[1,0,1]
	v_add_f32_dpp v86, v86, v86 quad_perm:[1,0,3,2] row_mask:0xf bank_mask:0xf bound_ctrl:1
	v_add_f32_dpp v93, v93, v93 quad_perm:[1,0,3,2] row_mask:0xf bank_mask:0xf bound_ctrl:1
	ds_read_b128 v[26:29], v199 offset:10176
	v_add_f32_dpp v86, v86, v86 quad_perm:[2,3,0,1] row_mask:0xf bank_mask:0xf bound_ctrl:1
	v_add_f32_dpp v93, v93, v93 quad_perm:[2,3,0,1] row_mask:0xf bank_mask:0xf bound_ctrl:1
	ds_read_b128 v[30:33], v199 offset:10192
	v_add_f32_dpp v86, v86, v86 row_half_mirror row_mask:0xf bank_mask:0xf bound_ctrl:1
	v_add_f32_dpp v93, v93, v93 row_half_mirror row_mask:0xf bank_mask:0xf bound_ctrl:1
	v_pk_fma_f32 v[164:165], v[78:79], v[84:85], v[96:97] op_sel_hi:[1,0,1]
	v_pk_fma_f32 v[166:167], v[80:81], v[84:85], v[98:99] op_sel_hi:[1,0,1]
	v_pk_fma_f32 v[168:169], v[82:83], v[84:85], v[100:101] op_sel_hi:[1,0,1]
	s_waitcnt lgkmcnt(10)
; template <int CPL>
; DI void scan_block2(CP p, int layer, int s, int d, int hd, int rowhalf, char* smem) {
;     ...
;       for (int jj = 0; jj < nst; ++jj) {
;         float4 na[CPL / 4], ny[CPL / 4], nw[CPL / 4], nb[CPL / 4], nk[CPL / 4];
;         float nvv;
;         {
;           const int jn = jj + 1;
;           const float* o = ob + jn * 392 + cg * CPL;
; #pragma unroll
;           for (int i = 0; i < CPL / 4; ++i) {
;             na[i] = *(const float4*)(o + 4 * i); ny[i] = *(const float4*)(o + 64 + 4 * i); nw[i] = *(const float4*)(o + 128 + 4 * i);
;             nb[i] = *(const float4*)(o + 192 + 4 * i); nk[i] = *(const float4*)(o + 256 + 4 * i);
;           }
;           nvv = ob[jn * 392 + 320 + row];
;         }
;         f2 A[NV], Y[NV], W[NV], B[NV], K[NV];
; #pragma unroll
;         for (int i = 0; i < CPL / 4; ++i) {
;           A[2 * i] = mk2(ca[i].x, ca[i].y); A[2 * i + 1] = mk2(ca[i].z, ca[i].w);
;           Y[2 * i] = mk2(cy[i].x, cy[i].y); Y[2 * i + 1] = mk2(cy[i].z, cy[i].w);
;           W[2 * i] = mk2(cw[i].x, cw[i].y); W[2 * i + 1] = mk2(cw[i].z, cw[i].w);
;           B[2 * i] = mk2(cb[i].x, cb[i].y); B[2 * i + 1] = mk2(cb[i].z, cb[i].w);
;           K[2 * i] = mk2(ck[i].x, ck[i].y); K[2 * i + 1] = mk2(ck[i].z, ck[i].w);
;         }
;         const float vv = cvv;
;         f2 pa0 = S[0] * A[0], pa1 = S[1] * A[1];
; #pragma unroll
;         for (int i = 2; i < NV; i += 2) { pa0 = S[i] * A[i] + pa0; pa1 = S[i + 1] * A[i + 1] + pa1; }
;         pa0 = pa0 + pa1;
;         float da = pa0.x + pa0.y;
;         const f2 vvv = mk2(vv, vv);
;         f2 SW[NV];
; #pragma unroll
;         for (int i = 0; i < NV; ++i) SW[i] = S[i] * W[i] + vvv * K[i];
;         da += __int_as_float(__builtin_amdgcn_update_dpp(0, __float_as_int(da), 0xB1, 0xf, 0xf, false));
;         da += __int_as_float(__builtin_amdgcn_update_dpp(0, __float_as_int(da), 0x4E, 0xf, 0xf, false));
;         if (CPL == 8) da += __int_as_float(__builtin_amdgcn_update_dpp(0, __float_as_int(da), 0x141, 0xf, 0xf, false));
;         const f2 dav = mk2(da, da);
; #pragma unroll
;         for (int i = 0; i < NV; ++i) S[i] = dav * B[i] + SW[i];
;         f2 py0 = S[0] * Y[0], py1 = S[1] * Y[1];
; #pragma unroll
;         for (int i = 2; i < NV; i += 2) { py0 = S[i] * Y[i] + py0; py1 = S[i + 1] * Y[i + 1] + py1; }
;         py0 = py0 + py1;
;         float yv = py0.x + py0.y;
	v_pk_fma_f32 v[170:171], v[68:69], v[86:87], v[162:163] op_sel_hi:[1,0,1]
	v_pk_fma_f32 v[172:173], v[70:71], v[86:87], v[164:165] op_sel_hi:[1,0,1]
	v_pk_fma_f32 v[174:175], v[72:73], v[86:87], v[166:167] op_sel_hi:[1,0,1]
	v_pk_fma_f32 v[176:177], v[74:75], v[86:87], v[168:169] op_sel_hi:[1,0,1]
	ds_write_b32 v201, v93 offset:768
	v_pk_mul_f32 v[90:91], v[10:11], v[94:95]
	v_pk_fma_f32 v[90:91], v[12:13], v[96:97], v[90:91]
	v_pk_fma_f32 v[90:91], v[14:15], v[98:99], v[90:91]
	v_pk_fma_f32 v[90:91], v[16:17], v[100:101], v[90:91]
	ds_read_b128 v[10:13], v199 offset:9664
	v_add_f32_e32 v92, v90, v91
	ds_read_b128 v[14:17], v199 offset:9680
	s_waitcnt lgkmcnt(5)
	v_pk_mul_f32 v[88:89], v[2:3], v[170:171]
	ds_read_b128 v[44:47], v199 offset:10976
	v_pk_fma_f32 v[88:89], v[4:5], v[172:173], v[88:89]
	ds_read_b128 v[48:51], v199 offset:10992
	v_pk_fma_f32 v[88:89], v[6:7], v[174:175], v[88:89]
	ds_read_b128 v[76:79], v199 offset:12000
	v_pk_fma_f32 v[88:89], v[8:9], v[176:177], v[88:89]
	ds_read_b128 v[80:83], v199 offset:12016
	v_add_f32_e32 v86, v88, v89
	ds_read_b32 v84, v200 offset:10976
	v_pk_fma_f32 v[162:163], v[34:35], v[42:43], v[170:171] op_sel_hi:[1,0,1]
	v_add_f32_dpp v86, v86, v86 quad_perm:[1,0,3,2] row_mask:0xf bank_mask:0xf bound_ctrl:1
	v_add_f32_dpp v92, v92, v92 quad_perm:[1,0,3,2] row_mask:0xf bank_mask:0xf bound_ctrl:1
	ds_read_b128 v[68:71], v199 offset:11744
	v_add_f32_dpp v86, v86, v86 quad_perm:[2,3,0,1] row_mask:0xf bank_mask:0xf bound_ctrl:1
	v_add_f32_dpp v92, v92, v92 quad_perm:[2,3,0,1] row_mask:0xf bank_mask:0xf bound_ctrl:1
	ds_read_b128 v[72:75], v199 offset:11760
	v_add_f32_dpp v86, v86, v86 row_half_mirror row_mask:0xf bank_mask:0xf bound_ctrl:1
	v_add_f32_dpp v92, v92, v92 row_half_mirror row_mask:0xf bank_mask:0xf bound_ctrl:1
	v_pk_fma_f32 v[164:165], v[36:37], v[42:43], v[172:173] op_sel_hi:[1,0,1]
	v_pk_fma_f32 v[166:167], v[38:39], v[42:43], v[174:175] op_sel_hi:[1,0,1]
	v_pk_fma_f32 v[168:169], v[40:41], v[42:43], v[176:177] op_sel_hi:[1,0,1]
	s_waitcnt lgkmcnt(10)
	v_pk_fma_f32 v[94:95], v[26:27], v[86:87], v[162:163] op_sel_hi:[1,0,1]
	v_pk_fma_f32 v[96:97], v[28:29], v[86:87], v[164:165] op_sel_hi:[1,0,1]
	v_pk_fma_f32 v[98:99], v[30:31], v[86:87], v[166:167] op_sel_hi:[1,0,1]
	v_pk_fma_f32 v[100:101], v[32:33], v[86:87], v[168:169] op_sel_hi:[1,0,1]
	ds_write_b32 v201, v92 offset:1024
	v_pk_mul_f32 v[90:91], v[52:53], v[170:171]
	v_pk_fma_f32 v[90:91], v[54:55], v[172:173], v[90:91]
	v_pk_fma_f32 v[90:91], v[56:57], v[174:175], v[90:91]
	v_pk_fma_f32 v[90:91], v[58:59], v[176:177], v[90:91]
	ds_read_b128 v[52:55], v199 offset:11232
	v_add_f32_e32 v93, v90, v91
	ds_read_b128 v[56:59], v199 offset:11248
	s_waitcnt lgkmcnt(5)
	v_pk_mul_f32 v[88:89], v[44:45], v[94:95]
	ds_read_b128 v[2:5], v199 offset:12544
	v_pk_fma_f32 v[88:89], v[46:47], v[96:97], v[88:89]
	ds_read_b128 v[6:9], v199 offset:12560
	v_pk_fma_f32 v[88:89], v[48:49], v[98:99], v[88:89]
	ds_read_b128 v[34:37], v199 offset:13568
	v_pk_fma_f32 v[88:89], v[50:51], v[100:101], v[88:89]
	ds_read_b128 v[38:41], v199 offset:13584
	v_add_f32_e32 v86, v88, v89
	ds_read_b32 v42, v200 offset:12544
	ds_read_b128 v[18:21], v199 offset:11488
	ds_read_b128 v[22:25], v199 offset:11504
	v_add_f32_dpp v86, v86, v86 quad_perm:[1,0,3,2] row_mask:0xf bank_mask:0xf bound_ctrl:1
	v_add_f32_dpp v93, v93, v93 quad_perm:[1,0,3,2] row_mask:0xf bank_mask:0xf bound_ctrl:1
	ds_read_b128 v[26:29], v199 offset:13312
	v_add_f32_dpp v86, v86, v86 quad_perm:[2,3,0,1] row_mask:0xf bank_mask:0xf bound_ctrl:1
	v_add_f32_dpp v93, v93, v93 quad_perm:[2,3,0,1] row_mask:0xf bank_mask:0xf bound_ctrl:1
	ds_read_b128 v[30:33], v199 offset:13328
	v_add_f32_dpp v86, v86, v86 row_half_mirror row_mask:0xf bank_mask:0xf bound_ctrl:1
	v_add_f32_dpp v93, v93, v93 row_half_mirror row_mask:0xf bank_mask:0xf bound_ctrl:1
	v_pk_fma_f32 v[162:163], v[76:77], v[84:85], v[94:95] op_sel_hi:[1,0,1]
	v_pk_fma_f32 v[164:165], v[78:79], v[84:85], v[96:97] op_sel_hi:[1,0,1]
	v_pk_fma_f32 v[166:167], v[80:81], v[84:85], v[98:99] op_sel_hi:[1,0,1]
	v_pk_fma_f32 v[168:169], v[82:83], v[84:85], v[100:101] op_sel_hi:[1,0,1]
	s_waitcnt lgkmcnt(12)
	v_pk_fma_f32 v[170:171], v[68:69], v[86:87], v[162:163] op_sel_hi:[1,0,1]
	v_pk_fma_f32 v[172:173], v[70:71], v[86:87], v[164:165] op_sel_hi:[1,0,1]
	v_pk_fma_f32 v[174:175], v[72:73], v[86:87], v[166:167] op_sel_hi:[1,0,1]
	v_pk_fma_f32 v[176:177], v[74:75], v[86:87], v[168:169] op_sel_hi:[1,0,1]
	s_waitcnt lgkmcnt(2)
	v_pk_mul_f32 v[170:171], v[170:171], v[18:19]
	v_pk_mul_f32 v[172:173], v[172:173], v[20:21]
	v_pk_mul_f32 v[174:175], v[174:175], v[22:23]
	v_pk_mul_f32 v[176:177], v[176:177], v[24:25]
	ds_write_b32 v201, v93 offset:1280
	v_pk_mul_f32 v[90:91], v[10:11], v[94:95]
	v_pk_fma_f32 v[90:91], v[12:13], v[96:97], v[90:91]
	v_pk_fma_f32 v[90:91], v[14:15], v[98:99], v[90:91]
	v_pk_fma_f32 v[90:91], v[16:17], v[100:101], v[90:91]
	ds_read_b128 v[10:13], v199 offset:12800
	v_add_f32_e32 v92, v90, v91
	ds_read_b128 v[14:17], v199 offset:12816
	s_waitcnt lgkmcnt(7)
; template <int CPL>
; DI void scan_block2(CP p, int layer, int s, int d, int hd, int rowhalf, char* smem) {
;     ...
;       for (int jj = 0; jj < nst; ++jj) {
;         float4 na[CPL / 4], ny[CPL / 4], nw[CPL / 4], nb[CPL / 4], nk[CPL / 4];
;         float nvv;
;         {
;           const int jn = jj + 1;
;           const float* o = ob + jn * 392 + cg * CPL;
; #pragma unroll
;           for (int i = 0; i < CPL / 4; ++i) {
;             na[i] = *(const float4*)(o + 4 * i); ny[i] = *(const float4*)(o + 64 + 4 * i); nw[i] = *(const float4*)(o + 128 + 4 * i);
;             nb[i] = *(const float4*)(o + 192 + 4 * i); nk[i] = *(const float4*)(o + 256 + 4 * i);
;           }
;           nvv = ob[jn * 392 + 320 + row];
;         }
;         f2 A[NV], Y[NV], W[NV], B[NV], K[NV];
; #pragma unroll
;         for (int i = 0; i < CPL / 4; ++i) {
;           A[2 * i] = mk2(ca[i].x, ca[i].y); A[2 * i + 1] = mk2(ca[i].z, ca[i].w);
;           Y[2 * i] = mk2(cy[i].x, cy[i].y); Y[2 * i + 1] = mk2(cy[i].z, cy[i].w);
;           W[2 * i] = mk2(cw[i].x, cw[i].y); W[2 * i + 1] = mk2(cw[i].z, cw[i].w);
;           B[2 * i] = mk2(cb[i].x, cb[i].y); B[2 * i + 1] = mk2(cb[i].z, cb[i].w);
;           K[2 * i] = mk2(ck[i].x, ck[i].y); K[2 * i + 1] = mk2(ck[i].z, ck[i].w);
;         }
;         const float vv = cvv;
;         f2 pa0 = S[0] * A[0], pa1 = S[1] * A[1];
; #pragma unroll
;         for (int i = 2; i < NV; i += 2) { pa0 = S[i] * A[i] + pa0; pa1 = S[i + 1] * A[i + 1] + pa1; }
;         pa0 = pa0 + pa1;
;         float da = pa0.x + pa0.y;
;         const f2 vvv = mk2(vv, vv);
;         f2 SW[NV];
; #pragma unroll
;         for (int i = 0; i < NV; ++i) SW[i] = S[i] * W[i] + vvv * K[i];
;         da += __int_as_float(__builtin_amdgcn_update_dpp(0, __float_as_int(da), 0xB1, 0xf, 0xf, false));
;         da += __int_as_float(__builtin_amdgcn_update_dpp(0, __float_as_int(da), 0x4E, 0xf, 0xf, false));
;         if (CPL == 8) da += __int_as_float(__builtin_amdgcn_update_dpp(0, __float_as_int(da), 0x141, 0xf, 0xf, false));
;         const f2 dav = mk2(da, da);
; #pragma unroll
;         for (int i = 0; i < NV; ++i) S[i] = dav * B[i] + SW[i];
;         f2 py0 = S[0] * Y[0], py1 = S[1] * Y[1];
; #pragma unroll
;         for (int i = 2; i < NV; i += 2) { py0 = S[i] * Y[i] + py0; py1 = S[i + 1] * Y[i + 1] + py1; }
;         py0 = py0 + py1;
;         float yv = py0.x + py0.y;
	v_pk_mul_f32 v[88:89], v[2:3], v[170:171]
	ds_read_b128 v[44:47], v199 offset:14112
	v_pk_fma_f32 v[88:89], v[4:5], v[172:173], v[88:89]
	ds_read_b128 v[48:51], v199 offset:14128
	v_pk_fma_f32 v[88:89], v[6:7], v[174:175], v[88:89]
	ds_read_b128 v[76:79], v199 offset:15136
	v_pk_fma_f32 v[88:89], v[8:9], v[176:177], v[88:89]
	ds_read_b128 v[80:83], v199 offset:15152
	v_add_f32_e32 v86, v88, v89
	ds_read_b32 v84, v200 offset:14112
	v_pk_fma_f32 v[162:163], v[34:35], v[42:43], v[170:171] op_sel_hi:[1,0,1]
	v_add_f32_dpp v86, v86, v86 quad_perm:[1,0,3,2] row_mask:0xf bank_mask:0xf bound_ctrl:1
	v_add_f32_dpp v92, v92, v92 quad_perm:[1,0,3,2] row_mask:0xf bank_mask:0xf bound_ctrl:1
	ds_read_b128 v[68:71], v199 offset:14880
	v_add_f32_dpp v86, v86, v86 quad_perm:[2,3,0,1] row_mask:0xf bank_mask:0xf bound_ctrl:1
	v_add_f32_dpp v92, v92, v92 quad_perm:[2,3,0,1] row_mask:0xf bank_mask:0xf bound_ctrl:1
	ds_read_b128 v[72:75], v199 offset:14896
	v_add_f32_dpp v86, v86, v86 row_half_mirror row_mask:0xf bank_mask:0xf bound_ctrl:1
	v_add_f32_dpp v92, v92, v92 row_half_mirror row_mask:0xf bank_mask:0xf bound_ctrl:1
	v_pk_fma_f32 v[164:165], v[36:37], v[42:43], v[172:173] op_sel_hi:[1,0,1]
	v_pk_fma_f32 v[166:167], v[38:39], v[42:43], v[174:175] op_sel_hi:[1,0,1]
	v_pk_fma_f32 v[168:169], v[40:41], v[42:43], v[176:177] op_sel_hi:[1,0,1]
	s_waitcnt lgkmcnt(10)
	v_pk_fma_f32 v[94:95], v[26:27], v[86:87], v[162:163] op_sel_hi:[1,0,1]
	v_pk_fma_f32 v[96:97], v[28:29], v[86:87], v[164:165] op_sel_hi:[1,0,1]
	v_pk_fma_f32 v[98:99], v[30:31], v[86:87], v[166:167] op_sel_hi:[1,0,1]
	v_pk_fma_f32 v[100:101], v[32:33], v[86:87], v[168:169] op_sel_hi:[1,0,1]
	ds_write_b32 v201, v92 offset:1536
	v_pk_mul_f32 v[90:91], v[52:53], v[170:171]
	v_pk_fma_f32 v[90:91], v[54:55], v[172:173], v[90:91]
	v_pk_fma_f32 v[90:91], v[56:57], v[174:175], v[90:91]
	v_pk_fma_f32 v[90:91], v[58:59], v[176:177], v[90:91]
	ds_read_b128 v[52:55], v199 offset:14368
	v_add_f32_e32 v93, v90, v91
	ds_read_b128 v[56:59], v199 offset:14384
	s_waitcnt lgkmcnt(5)
	v_pk_mul_f32 v[88:89], v[44:45], v[94:95]
	ds_read_b128 v[2:5], v199 offset:15680
	v_pk_fma_f32 v[88:89], v[46:47], v[96:97], v[88:89]
	ds_read_b128 v[6:9], v199 offset:15696
	v_pk_fma_f32 v[88:89], v[48:49], v[98:99], v[88:89]
	ds_read_b128 v[34:37], v199 offset:16704
	v_pk_fma_f32 v[88:89], v[50:51], v[100:101], v[88:89]
	ds_read_b128 v[38:41], v199 offset:16720
	v_add_f32_e32 v86, v88, v89
	ds_read_b32 v42, v200 offset:15680
	v_pk_fma_f32 v[162:163], v[76:77], v[84:85], v[94:95] op_sel_hi:[1,0,1]
	v_add_f32_dpp v86, v86, v86 quad_perm:[1,0,3,2] row_mask:0xf bank_mask:0xf bound_ctrl:1
	v_add_f32_dpp v93, v93, v93 quad_perm:[1,0,3,2] row_mask:0xf bank_mask:0xf bound_ctrl:1
	ds_read_b128 v[26:29], v199 offset:16448
	v_add_f32_dpp v86, v86, v86 quad_perm:[2,3,0,1] row_mask:0xf bank_mask:0xf bound_ctrl:1
	v_add_f32_dpp v93, v93, v93 quad_perm:[2,3,0,1] row_mask:0xf bank_mask:0xf bound_ctrl:1
	ds_read_b128 v[30:33], v199 offset:16464
	v_add_f32_dpp v86, v86, v86 row_half_mirror row_mask:0xf bank_mask:0xf bound_ctrl:1
	v_add_f32_dpp v93, v93, v93 row_half_mirror row_mask:0xf bank_mask:0xf bound_ctrl:1
	v_pk_fma_f32 v[164:165], v[78:79], v[84:85], v[96:97] op_sel_hi:[1,0,1]
	v_pk_fma_f32 v[166:167], v[80:81], v[84:85], v[98:99] op_sel_hi:[1,0,1]
	v_pk_fma_f32 v[168:169], v[82:83], v[84:85], v[100:101] op_sel_hi:[1,0,1]
	s_waitcnt lgkmcnt(10)
	v_pk_fma_f32 v[170:171], v[68:69], v[86:87], v[162:163] op_sel_hi:[1,0,1]
	v_pk_fma_f32 v[172:173], v[70:71], v[86:87], v[164:165] op_sel_hi:[1,0,1]
	v_pk_fma_f32 v[174:175], v[72:73], v[86:87], v[166:167] op_sel_hi:[1,0,1]
	v_pk_fma_f32 v[176:177], v[74:75], v[86:87], v[168:169] op_sel_hi:[1,0,1]
	ds_write_b32 v201, v93 offset:1792
	v_pk_mul_f32 v[90:91], v[10:11], v[94:95]
	v_pk_fma_f32 v[90:91], v[12:13], v[96:97], v[90:91]
	v_pk_fma_f32 v[90:91], v[14:15], v[98:99], v[90:91]
	v_pk_fma_f32 v[90:91], v[16:17], v[100:101], v[90:91]
	ds_read_b128 v[10:13], v199 offset:15936
	v_add_f32_e32 v92, v90, v91
	ds_read_b128 v[14:17], v199 offset:15952
	s_waitcnt lgkmcnt(5)
	v_pk_mul_f32 v[88:89], v[2:3], v[170:171]
	ds_read_b128 v[44:47], v199 offset:17248
	v_pk_fma_f32 v[88:89], v[4:5], v[172:173], v[88:89]
	ds_read_b128 v[48:51], v199 offset:17264
	v_pk_fma_f32 v[88:89], v[6:7], v[174:175], v[88:89]
	ds_read_b128 v[76:79], v199 offset:18272
	v_pk_fma_f32 v[88:89], v[8:9], v[176:177], v[88:89]
	ds_read_b128 v[80:83], v199 offset:18288
	v_add_f32_e32 v86, v88, v89
	ds_read_b32 v84, v200 offset:17248
	v_pk_fma_f32 v[162:163], v[34:35], v[42:43], v[170:171] op_sel_hi:[1,0,1]
	v_add_f32_dpp v86, v86, v86 quad_perm:[1,0,3,2] row_mask:0xf bank_mask:0xf bound_ctrl:1
	v_add_f32_dpp v92, v92, v92 quad_perm:[1,0,3,2] row_mask:0xf bank_mask:0xf bound_ctrl:1
	ds_read_b128 v[68:71], v199 offset:18016
	v_add_f32_dpp v86, v86, v86 quad_perm:[2,3,0,1] row_mask:0xf bank_mask:0xf bound_ctrl:1
	v_add_f32_dpp v92, v92, v92 quad_perm:[2,3,0,1] row_mask:0xf bank_mask:0xf bound_ctrl:1
	ds_read_b128 v[72:75], v199 offset:18032
	v_add_f32_dpp v86, v86, v86 row_half_mirror row_mask:0xf bank_mask:0xf bound_ctrl:1
	v_add_f32_dpp v92, v92, v92 row_half_mirror row_mask:0xf bank_mask:0xf bound_ctrl:1
	v_pk_fma_f32 v[164:165], v[36:37], v[42:43], v[172:173] op_sel_hi:[1,0,1]
	v_pk_fma_f32 v[166:167], v[38:39], v[42:43], v[174:175] op_sel_hi:[1,0,1]
	v_pk_fma_f32 v[168:169], v[40:41], v[42:43], v[176:177] op_sel_hi:[1,0,1]
	s_waitcnt lgkmcnt(10)
; template <int CPL>
; DI void scan_block2(CP p, int layer, int s, int d, int hd, int rowhalf, char* smem) {
;     ...
;       for (int jj = 0; jj < nst; ++jj) {
;         float4 na[CPL / 4], ny[CPL / 4], nw[CPL / 4], nb[CPL / 4], nk[CPL / 4];
;         float nvv;
;         {
;           const int jn = jj + 1;
;           const float* o = ob + jn * 392 + cg * CPL;
; #pragma unroll
;           for (int i = 0; i < CPL / 4; ++i) {
;             na[i] = *(const float4*)(o + 4 * i); ny[i] = *(const float4*)(o + 64 + 4 * i); nw[i] = *(const float4*)(o + 128 + 4 * i);
;             nb[i] = *(const float4*)(o + 192 + 4 * i); nk[i] = *(const float4*)(o + 256 + 4 * i);
;           }
;           nvv = ob[jn * 392 + 320 + row];
;         }
;         f2 A[NV], Y[NV], W[NV], B[NV], K[NV];
; #pragma unroll
;         for (int i = 0; i < CPL / 4; ++i) {
;           A[2 * i] = mk2(ca[i].x, ca[i].y); A[2 * i + 1] = mk2(ca[i].z, ca[i].w);
;           Y[2 * i] = mk2(cy[i].x, cy[i].y); Y[2 * i + 1] = mk2(cy[i].z, cy[i].w);
;           W[2 * i] = mk2(cw[i].x, cw[i].y); W[2 * i + 1] = mk2(cw[i].z, cw[i].w);
;           B[2 * i] = mk2(cb[i].x, cb[i].y); B[2 * i + 1] = mk2(cb[i].z, cb[i].w);
;           K[2 * i] = mk2(ck[i].x, ck[i].y); K[2 * i + 1] = mk2(ck[i].z, ck[i].w);
;         }
;         const float vv = cvv;
;         f2 pa0 = S[0] * A[0], pa1 = S[1] * A[1];
; #pragma unroll
;         for (int i = 2; i < NV; i += 2) { pa0 = S[i] * A[i] + pa0; pa1 = S[i + 1] * A[i + 1] + pa1; }
;         pa0 = pa0 + pa1;
;         float da = pa0.x + pa0.y;
;         const f2 vvv = mk2(vv, vv);
;         f2 SW[NV];
; #pragma unroll
;         for (int i = 0; i < NV; ++i) SW[i] = S[i] * W[i] + vvv * K[i];
;         da += __int_as_float(__builtin_amdgcn_update_dpp(0, __float_as_int(da), 0xB1, 0xf, 0xf, false));
;         da += __int_as_float(__builtin_amdgcn_update_dpp(0, __float_as_int(da), 0x4E, 0xf, 0xf, false));
;         if (CPL == 8) da += __int_as_float(__builtin_amdgcn_update_dpp(0, __float_as_int(da), 0x141, 0xf, 0xf, false));
;         const f2 dav = mk2(da, da);
; #pragma unroll
;         for (int i = 0; i < NV; ++i) S[i] = dav * B[i] + SW[i];
;         f2 py0 = S[0] * Y[0], py1 = S[1] * Y[1];
; #pragma unroll
;         for (int i = 2; i < NV; i += 2) { py0 = S[i] * Y[i] + py0; py1 = S[i + 1] * Y[i + 1] + py1; }
;         py0 = py0 + py1;
;         float yv = py0.x + py0.y;
	v_pk_fma_f32 v[94:95], v[26:27], v[86:87], v[162:163] op_sel_hi:[1,0,1]
	v_pk_fma_f32 v[96:97], v[28:29], v[86:87], v[164:165] op_sel_hi:[1,0,1]
	v_pk_fma_f32 v[98:99], v[30:31], v[86:87], v[166:167] op_sel_hi:[1,0,1]
	v_pk_fma_f32 v[100:101], v[32:33], v[86:87], v[168:169] op_sel_hi:[1,0,1]
	ds_write_b32 v201, v92 offset:2048
	v_pk_mul_f32 v[90:91], v[52:53], v[170:171]
	v_pk_fma_f32 v[90:91], v[54:55], v[172:173], v[90:91]
	v_pk_fma_f32 v[90:91], v[56:57], v[174:175], v[90:91]
	v_pk_fma_f32 v[90:91], v[58:59], v[176:177], v[90:91]
	ds_read_b128 v[52:55], v199 offset:17504
	v_add_f32_e32 v93, v90, v91
	ds_read_b128 v[56:59], v199 offset:17520
	s_waitcnt lgkmcnt(5)
	v_pk_mul_f32 v[88:89], v[44:45], v[94:95]
	ds_read_b128 v[2:5], v199 offset:18816
	v_pk_fma_f32 v[88:89], v[46:47], v[96:97], v[88:89]
	ds_read_b128 v[6:9], v199 offset:18832
	v_pk_fma_f32 v[88:89], v[48:49], v[98:99], v[88:89]
	ds_read_b128 v[34:37], v199 offset:19840
	v_pk_fma_f32 v[88:89], v[50:51], v[100:101], v[88:89]
	ds_read_b128 v[38:41], v199 offset:19856
	v_add_f32_e32 v86, v88, v89
	ds_read_b32 v42, v200 offset:18816
	v_pk_fma_f32 v[162:163], v[76:77], v[84:85], v[94:95] op_sel_hi:[1,0,1]
	v_add_f32_dpp v86, v86, v86 quad_perm:[1,0,3,2] row_mask:0xf bank_mask:0xf bound_ctrl:1
	v_add_f32_dpp v93, v93, v93 quad_perm:[1,0,3,2] row_mask:0xf bank_mask:0xf bound_ctrl:1
	ds_read_b128 v[26:29], v199 offset:19584
	v_add_f32_dpp v86, v86, v86 quad_perm:[2,3,0,1] row_mask:0xf bank_mask:0xf bound_ctrl:1
	v_add_f32_dpp v93, v93, v93 quad_perm:[2,3,0,1] row_mask:0xf bank_mask:0xf bound_ctrl:1
	ds_read_b128 v[30:33], v199 offset:19600
	v_add_f32_dpp v86, v86, v86 row_half_mirror row_mask:0xf bank_mask:0xf bound_ctrl:1
	v_add_f32_dpp v93, v93, v93 row_half_mirror row_mask:0xf bank_mask:0xf bound_ctrl:1
	v_pk_fma_f32 v[164:165], v[78:79], v[84:85], v[96:97] op_sel_hi:[1,0,1]
	v_pk_fma_f32 v[166:167], v[80:81], v[84:85], v[98:99] op_sel_hi:[1,0,1]
	v_pk_fma_f32 v[168:169], v[82:83], v[84:85], v[100:101] op_sel_hi:[1,0,1]
	s_waitcnt lgkmcnt(10)
	v_pk_fma_f32 v[170:171], v[68:69], v[86:87], v[162:163] op_sel_hi:[1,0,1]
	v_pk_fma_f32 v[172:173], v[70:71], v[86:87], v[164:165] op_sel_hi:[1,0,1]
	v_pk_fma_f32 v[174:175], v[72:73], v[86:87], v[166:167] op_sel_hi:[1,0,1]
	v_pk_fma_f32 v[176:177], v[74:75], v[86:87], v[168:169] op_sel_hi:[1,0,1]
	ds_write_b32 v201, v93 offset:2304
	v_pk_mul_f32 v[90:91], v[10:11], v[94:95]
	v_pk_fma_f32 v[90:91], v[12:13], v[96:97], v[90:91]
	v_pk_fma_f32 v[90:91], v[14:15], v[98:99], v[90:91]
	v_pk_fma_f32 v[90:91], v[16:17], v[100:101], v[90:91]
	ds_read_b128 v[10:13], v199 offset:19072
	v_add_f32_e32 v92, v90, v91
	ds_read_b128 v[14:17], v199 offset:19088
	s_waitcnt lgkmcnt(5)
	v_pk_mul_f32 v[88:89], v[2:3], v[170:171]
	ds_read_b128 v[44:47], v199 offset:20384
	v_pk_fma_f32 v[88:89], v[4:5], v[172:173], v[88:89]
	ds_read_b128 v[48:51], v199 offset:20400
	v_pk_fma_f32 v[88:89], v[6:7], v[174:175], v[88:89]
	ds_read_b128 v[76:79], v199 offset:21408
	v_pk_fma_f32 v[88:89], v[8:9], v[176:177], v[88:89]
	ds_read_b128 v[80:83], v199 offset:21424
	v_add_f32_e32 v86, v88, v89
	ds_read_b32 v84, v200 offset:20384
	v_pk_fma_f32 v[162:163], v[34:35], v[42:43], v[170:171] op_sel_hi:[1,0,1]
	v_add_f32_dpp v86, v86, v86 quad_perm:[1,0,3,2] row_mask:0xf bank_mask:0xf bound_ctrl:1
	v_add_f32_dpp v92, v92, v92 quad_perm:[1,0,3,2] row_mask:0xf bank_mask:0xf bound_ctrl:1
	ds_read_b128 v[68:71], v199 offset:21152
	v_add_f32_dpp v86, v86, v86 quad_perm:[2,3,0,1] row_mask:0xf bank_mask:0xf bound_ctrl:1
	v_add_f32_dpp v92, v92, v92 quad_perm:[2,3,0,1] row_mask:0xf bank_mask:0xf bound_ctrl:1
	ds_read_b128 v[72:75], v199 offset:21168
	v_add_f32_dpp v86, v86, v86 row_half_mirror row_mask:0xf bank_mask:0xf bound_ctrl:1
	v_add_f32_dpp v92, v92, v92 row_half_mirror row_mask:0xf bank_mask:0xf bound_ctrl:1
	v_pk_fma_f32 v[164:165], v[36:37], v[42:43], v[172:173] op_sel_hi:[1,0,1]
	v_pk_fma_f32 v[166:167], v[38:39], v[42:43], v[174:175] op_sel_hi:[1,0,1]
	v_pk_fma_f32 v[168:169], v[40:41], v[42:43], v[176:177] op_sel_hi:[1,0,1]
	s_waitcnt lgkmcnt(10)
	v_pk_fma_f32 v[94:95], v[26:27], v[86:87], v[162:163] op_sel_hi:[1,0,1]
	v_pk_fma_f32 v[96:97], v[28:29], v[86:87], v[164:165] op_sel_hi:[1,0,1]
	v_pk_fma_f32 v[98:99], v[30:31], v[86:87], v[166:167] op_sel_hi:[1,0,1]
	v_pk_fma_f32 v[100:101], v[32:33], v[86:87], v[168:169] op_sel_hi:[1,0,1]
	ds_write_b32 v201, v92 offset:2560
	v_pk_mul_f32 v[90:91], v[52:53], v[170:171]
	v_pk_fma_f32 v[90:91], v[54:55], v[172:173], v[90:91]
	v_pk_fma_f32 v[90:91], v[56:57], v[174:175], v[90:91]
	v_pk_fma_f32 v[90:91], v[58:59], v[176:177], v[90:91]
	ds_read_b128 v[52:55], v199 offset:20640
	v_add_f32_e32 v93, v90, v91
	ds_read_b128 v[56:59], v199 offset:20656
	s_waitcnt lgkmcnt(5)
	v_pk_mul_f32 v[88:89], v[44:45], v[94:95]
	ds_read_b128 v[2:5], v199 offset:21952
	v_pk_fma_f32 v[88:89], v[46:47], v[96:97], v[88:89]
	ds_read_b128 v[6:9], v199 offset:21968
	v_pk_fma_f32 v[88:89], v[48:49], v[98:99], v[88:89]
	ds_read_b128 v[34:37], v199 offset:22976
	v_pk_fma_f32 v[88:89], v[50:51], v[100:101], v[88:89]
	ds_read_b128 v[38:41], v199 offset:22992
	v_add_f32_e32 v86, v88, v89
	ds_read_b32 v42, v200 offset:21952
	v_pk_fma_f32 v[162:163], v[76:77], v[84:85], v[94:95] op_sel_hi:[1,0,1]
	v_add_f32_dpp v86, v86, v86 quad_perm:[1,0,3,2] row_mask:0xf bank_mask:0xf bound_ctrl:1
	v_add_f32_dpp v93, v93, v93 quad_perm:[1,0,3,2] row_mask:0xf bank_mask:0xf bound_ctrl:1
	ds_read_b128 v[26:29], v199 offset:22720
	v_add_f32_dpp v86, v86, v86 quad_perm:[2,3,0,1] row_mask:0xf bank_mask:0xf bound_ctrl:1
	v_add_f32_dpp v93, v93, v93 quad_perm:[2,3,0,1] row_mask:0xf bank_mask:0xf bound_ctrl:1
	ds_read_b128 v[30:33], v199 offset:22736
	v_add_f32_dpp v86, v86, v86 row_half_mirror row_mask:0xf bank_mask:0xf bound_ctrl:1
	v_add_f32_dpp v93, v93, v93 row_half_mirror row_mask:0xf bank_mask:0xf bound_ctrl:1
	v_pk_fma_f32 v[164:165], v[78:79], v[84:85], v[96:97] op_sel_hi:[1,0,1]
	v_pk_fma_f32 v[166:167], v[80:81], v[84:85], v[98:99] op_sel_hi:[1,0,1]
	v_pk_fma_f32 v[168:169], v[82:83], v[84:85], v[100:101] op_sel_hi:[1,0,1]
	s_waitcnt lgkmcnt(10)
; template <int CPL>
; DI void scan_block2(CP p, int layer, int s, int d, int hd, int rowhalf, char* smem) {
;     ...
;       for (int jj = 0; jj < nst; ++jj) {
;         float4 na[CPL / 4], ny[CPL / 4], nw[CPL / 4], nb[CPL / 4], nk[CPL / 4];
;         float nvv;
;         {
;           const int jn = jj + 1;
;           const float* o = ob + jn * 392 + cg * CPL;
; #pragma unroll
;           for (int i = 0; i < CPL / 4; ++i) {
;             na[i] = *(const float4*)(o + 4 * i); ny[i] = *(const float4*)(o + 64 + 4 * i); nw[i] = *(const float4*)(o + 128 + 4 * i);
;             nb[i] = *(const float4*)(o + 192 + 4 * i); nk[i] = *(const float4*)(o + 256 + 4 * i);
;           }
;           nvv = ob[jn * 392 + 320 + row];
;         }
;         f2 A[NV], Y[NV], W[NV], B[NV], K[NV];
; #pragma unroll
;         for (int i = 0; i < CPL / 4; ++i) {
;           A[2 * i] = mk2(ca[i].x, ca[i].y); A[2 * i + 1] = mk2(ca[i].z, ca[i].w);
;           Y[2 * i] = mk2(cy[i].x, cy[i].y); Y[2 * i + 1] = mk2(cy[i].z, cy[i].w);
;           W[2 * i] = mk2(cw[i].x, cw[i].y); W[2 * i + 1] = mk2(cw[i].z, cw[i].w);
;           B[2 * i] = mk2(cb[i].x, cb[i].y); B[2 * i + 1] = mk2(cb[i].z, cb[i].w);
;           K[2 * i] = mk2(ck[i].x, ck[i].y); K[2 * i + 1] = mk2(ck[i].z, ck[i].w);
;         }
;         const float vv = cvv;
;         f2 pa0 = S[0] * A[0], pa1 = S[1] * A[1];
; #pragma unroll
;         for (int i = 2; i < NV; i += 2) { pa0 = S[i] * A[i] + pa0; pa1 = S[i + 1] * A[i + 1] + pa1; }
;         pa0 = pa0 + pa1;
;         float da = pa0.x + pa0.y;
;         const f2 vvv = mk2(vv, vv);
;         f2 SW[NV];
; #pragma unroll
;         for (int i = 0; i < NV; ++i) SW[i] = S[i] * W[i] + vvv * K[i];
;         da += __int_as_float(__builtin_amdgcn_update_dpp(0, __float_as_int(da), 0xB1, 0xf, 0xf, false));
;         da += __int_as_float(__builtin_amdgcn_update_dpp(0, __float_as_int(da), 0x4E, 0xf, 0xf, false));
;         if (CPL == 8) da += __int_as_float(__builtin_amdgcn_update_dpp(0, __float_as_int(da), 0x141, 0xf, 0xf, false));
;         const f2 dav = mk2(da, da);
; #pragma unroll
;         for (int i = 0; i < NV; ++i) S[i] = dav * B[i] + SW[i];
;         f2 py0 = S[0] * Y[0], py1 = S[1] * Y[1];
; #pragma unroll
;         for (int i = 2; i < NV; i += 2) { py0 = S[i] * Y[i] + py0; py1 = S[i + 1] * Y[i + 1] + py1; }
;         py0 = py0 + py1;
;         float yv = py0.x + py0.y;
	v_pk_fma_f32 v[170:171], v[68:69], v[86:87], v[162:163] op_sel_hi:[1,0,1]
	v_pk_fma_f32 v[172:173], v[70:71], v[86:87], v[164:165] op_sel_hi:[1,0,1]
	v_pk_fma_f32 v[174:175], v[72:73], v[86:87], v[166:167] op_sel_hi:[1,0,1]
	v_pk_fma_f32 v[176:177], v[74:75], v[86:87], v[168:169] op_sel_hi:[1,0,1]
	ds_write_b32 v201, v93 offset:2816
	v_pk_mul_f32 v[90:91], v[10:11], v[94:95]
	v_pk_fma_f32 v[90:91], v[12:13], v[96:97], v[90:91]
	v_pk_fma_f32 v[90:91], v[14:15], v[98:99], v[90:91]
	v_pk_fma_f32 v[90:91], v[16:17], v[100:101], v[90:91]
	ds_read_b128 v[10:13], v199 offset:22208
	v_add_f32_e32 v92, v90, v91
	ds_read_b128 v[14:17], v199 offset:22224
	s_waitcnt lgkmcnt(5)
	v_pk_mul_f32 v[88:89], v[2:3], v[170:171]
	ds_read_b128 v[44:47], v199 offset:23520
	v_pk_fma_f32 v[88:89], v[4:5], v[172:173], v[88:89]
	ds_read_b128 v[48:51], v199 offset:23536
	v_pk_fma_f32 v[88:89], v[6:7], v[174:175], v[88:89]
	ds_read_b128 v[76:79], v199 offset:24544
	v_pk_fma_f32 v[88:89], v[8:9], v[176:177], v[88:89]
	ds_read_b128 v[80:83], v199 offset:24560
	v_add_f32_e32 v86, v88, v89
	ds_read_b32 v84, v200 offset:23520
	v_pk_fma_f32 v[162:163], v[34:35], v[42:43], v[170:171] op_sel_hi:[1,0,1]
	v_add_f32_dpp v86, v86, v86 quad_perm:[1,0,3,2] row_mask:0xf bank_mask:0xf bound_ctrl:1
	v_add_f32_dpp v92, v92, v92 quad_perm:[1,0,3,2] row_mask:0xf bank_mask:0xf bound_ctrl:1
	ds_read_b128 v[68:71], v199 offset:24288
	v_add_f32_dpp v86, v86, v86 quad_perm:[2,3,0,1] row_mask:0xf bank_mask:0xf bound_ctrl:1
	v_add_f32_dpp v92, v92, v92 quad_perm:[2,3,0,1] row_mask:0xf bank_mask:0xf bound_ctrl:1
	ds_read_b128 v[72:75], v199 offset:24304
	v_add_f32_dpp v86, v86, v86 row_half_mirror row_mask:0xf bank_mask:0xf bound_ctrl:1
	v_add_f32_dpp v92, v92, v92 row_half_mirror row_mask:0xf bank_mask:0xf bound_ctrl:1
	v_pk_fma_f32 v[164:165], v[36:37], v[42:43], v[172:173] op_sel_hi:[1,0,1]
	v_pk_fma_f32 v[166:167], v[38:39], v[42:43], v[174:175] op_sel_hi:[1,0,1]
	v_pk_fma_f32 v[168:169], v[40:41], v[42:43], v[176:177] op_sel_hi:[1,0,1]
	s_waitcnt lgkmcnt(10)
	v_pk_fma_f32 v[94:95], v[26:27], v[86:87], v[162:163] op_sel_hi:[1,0,1]
	v_pk_fma_f32 v[96:97], v[28:29], v[86:87], v[164:165] op_sel_hi:[1,0,1]
	v_pk_fma_f32 v[98:99], v[30:31], v[86:87], v[166:167] op_sel_hi:[1,0,1]
	v_pk_fma_f32 v[100:101], v[32:33], v[86:87], v[168:169] op_sel_hi:[1,0,1]
	ds_write_b32 v201, v92 offset:3072
	v_pk_mul_f32 v[90:91], v[52:53], v[170:171]
	v_pk_fma_f32 v[90:91], v[54:55], v[172:173], v[90:91]
	v_pk_fma_f32 v[90:91], v[56:57], v[174:175], v[90:91]
	v_pk_fma_f32 v[90:91], v[58:59], v[176:177], v[90:91]
	ds_read_b128 v[52:55], v199 offset:23776
	v_add_f32_e32 v93, v90, v91
	ds_read_b128 v[56:59], v199 offset:23792
	s_waitcnt lgkmcnt(5)
	v_pk_mul_f32 v[88:89], v[44:45], v[94:95]
	ds_read_b128 v[2:5], v199 offset:25088
	v_pk_fma_f32 v[88:89], v[46:47], v[96:97], v[88:89]
	ds_read_b128 v[6:9], v199 offset:25104
	v_pk_fma_f32 v[88:89], v[48:49], v[98:99], v[88:89]
	ds_read_b128 v[34:37], v199 offset:26112
	v_pk_fma_f32 v[88:89], v[50:51], v[100:101], v[88:89]
	ds_read_b128 v[38:41], v199 offset:26128
	v_add_f32_e32 v86, v88, v89
	ds_read_b32 v42, v200 offset:25088
	ds_read_b128 v[18:21], v199 offset:24032
	ds_read_b128 v[22:25], v199 offset:24048
	v_add_f32_dpp v86, v86, v86 quad_perm:[1,0,3,2] row_mask:0xf bank_mask:0xf bound_ctrl:1
	v_add_f32_dpp v93, v93, v93 quad_perm:[1,0,3,2] row_mask:0xf bank_mask:0xf bound_ctrl:1
	ds_read_b128 v[26:29], v199 offset:25856
	v_add_f32_dpp v86, v86, v86 quad_perm:[2,3,0,1] row_mask:0xf bank_mask:0xf bound_ctrl:1
	v_add_f32_dpp v93, v93, v93 quad_perm:[2,3,0,1] row_mask:0xf bank_mask:0xf bound_ctrl:1
	ds_read_b128 v[30:33], v199 offset:25872
	v_add_f32_dpp v86, v86, v86 row_half_mirror row_mask:0xf bank_mask:0xf bound_ctrl:1
	v_add_f32_dpp v93, v93, v93 row_half_mirror row_mask:0xf bank_mask:0xf bound_ctrl:1
	v_pk_fma_f32 v[162:163], v[76:77], v[84:85], v[94:95] op_sel_hi:[1,0,1]
	v_pk_fma_f32 v[164:165], v[78:79], v[84:85], v[96:97] op_sel_hi:[1,0,1]
	v_pk_fma_f32 v[166:167], v[80:81], v[84:85], v[98:99] op_sel_hi:[1,0,1]
	v_pk_fma_f32 v[168:169], v[82:83], v[84:85], v[100:101] op_sel_hi:[1,0,1]
	s_waitcnt lgkmcnt(12)
	v_pk_fma_f32 v[170:171], v[68:69], v[86:87], v[162:163] op_sel_hi:[1,0,1]
	v_pk_fma_f32 v[172:173], v[70:71], v[86:87], v[164:165] op_sel_hi:[1,0,1]
	v_pk_fma_f32 v[174:175], v[72:73], v[86:87], v[166:167] op_sel_hi:[1,0,1]
	v_pk_fma_f32 v[176:177], v[74:75], v[86:87], v[168:169] op_sel_hi:[1,0,1]
	s_waitcnt lgkmcnt(2)
	v_pk_mul_f32 v[170:171], v[170:171], v[18:19]
	v_pk_mul_f32 v[172:173], v[172:173], v[20:21]
	v_pk_mul_f32 v[174:175], v[174:175], v[22:23]
	v_pk_mul_f32 v[176:177], v[176:177], v[24:25]
	ds_write_b32 v201, v93 offset:3328
	v_pk_mul_f32 v[90:91], v[10:11], v[94:95]
	v_pk_fma_f32 v[90:91], v[12:13], v[96:97], v[90:91]
	v_pk_fma_f32 v[90:91], v[14:15], v[98:99], v[90:91]
	v_pk_fma_f32 v[90:91], v[16:17], v[100:101], v[90:91]
	ds_read_b128 v[10:13], v199 offset:25344
	v_add_f32_e32 v92, v90, v91
	ds_read_b128 v[14:17], v199 offset:25360
	s_cmp_eq_u32 s10, 0x100
	s_cbranch_scc1 .Lsc8_drain16
; template <int CPL>
; DI void scan_block2(CP p, int layer, int s, int d, int hd, int rowhalf, char* smem) {
;     ...
;       for (int jj = 0; jj < nst; ++jj) {
;         float4 na[CPL / 4], ny[CPL / 4], nw[CPL / 4], nb[CPL / 4], nk[CPL / 4];
;         float nvv;
;         {
;           const int jn = jj + 1;
;           const float* o = ob + jn * 392 + cg * CPL;
; #pragma unroll
;           for (int i = 0; i < CPL / 4; ++i) {
;             na[i] = *(const float4*)(o + 4 * i); ny[i] = *(const float4*)(o + 64 + 4 * i); nw[i] = *(const float4*)(o + 128 + 4 * i);
;             nb[i] = *(const float4*)(o + 192 + 4 * i); nk[i] = *(const float4*)(o + 256 + 4 * i);
;           }
;           nvv = ob[jn * 392 + 320 + row];
;         }
;         f2 A[NV], Y[NV], W[NV], B[NV], K[NV];
; #pragma unroll
;         for (int i = 0; i < CPL / 4; ++i) {
;           A[2 * i] = mk2(ca[i].x, ca[i].y); A[2 * i + 1] = mk2(ca[i].z, ca[i].w);
;           Y[2 * i] = mk2(cy[i].x, cy[i].y); Y[2 * i + 1] = mk2(cy[i].z, cy[i].w);
;           W[2 * i] = mk2(cw[i].x, cw[i].y); W[2 * i + 1] = mk2(cw[i].z, cw[i].w);
;           B[2 * i] = mk2(cb[i].x, cb[i].y); B[2 * i + 1] = mk2(cb[i].z, cb[i].w);
;           K[2 * i] = mk2(ck[i].x, ck[i].y); K[2 * i + 1] = mk2(ck[i].z, ck[i].w);
;         }
;         const float vv = cvv;
;         f2 pa0 = S[0] * A[0], pa1 = S[1] * A[1];
; #pragma unroll
;         for (int i = 2; i < NV; i += 2) { pa0 = S[i] * A[i] + pa0; pa1 = S[i + 1] * A[i + 1] + pa1; }
;         pa0 = pa0 + pa1;
;         float da = pa0.x + pa0.y;
;         const f2 vvv = mk2(vv, vv);
;         f2 SW[NV];
; #pragma unroll
;         for (int i = 0; i < NV; ++i) SW[i] = S[i] * W[i] + vvv * K[i];
;         da += __int_as_float(__builtin_amdgcn_update_dpp(0, __float_as_int(da), 0xB1, 0xf, 0xf, false));
;         da += __int_as_float(__builtin_amdgcn_update_dpp(0, __float_as_int(da), 0x4E, 0xf, 0xf, false));
;         if (CPL == 8) da += __int_as_float(__builtin_amdgcn_update_dpp(0, __float_as_int(da), 0x141, 0xf, 0xf, false));
;         const f2 dav = mk2(da, da);
; #pragma unroll
;         for (int i = 0; i < NV; ++i) S[i] = dav * B[i] + SW[i];
;         f2 py0 = S[0] * Y[0], py1 = S[1] * Y[1];
; #pragma unroll
;         for (int i = 2; i < NV; i += 2) { py0 = S[i] * Y[i] + py0; py1 = S[i + 1] * Y[i + 1] + py1; }
;         py0 = py0 + py1;
;         float yv = py0.x + py0.y;
	s_waitcnt lgkmcnt(7)
	v_pk_mul_f32 v[88:89], v[2:3], v[170:171]
	ds_read_b128 v[44:47], v199 offset:26656
	v_pk_fma_f32 v[88:89], v[4:5], v[172:173], v[88:89]
	ds_read_b128 v[48:51], v199 offset:26672
	v_pk_fma_f32 v[88:89], v[6:7], v[174:175], v[88:89]
	ds_read_b128 v[76:79], v199 offset:27680
	v_pk_fma_f32 v[88:89], v[8:9], v[176:177], v[88:89]
	ds_read_b128 v[80:83], v199 offset:27696
	v_add_f32_e32 v86, v88, v89
	ds_read_b32 v84, v200 offset:26656
	v_pk_fma_f32 v[162:163], v[34:35], v[42:43], v[170:171] op_sel_hi:[1,0,1]
	v_add_f32_dpp v86, v86, v86 quad_perm:[1,0,3,2] row_mask:0xf bank_mask:0xf bound_ctrl:1
	v_add_f32_dpp v92, v92, v92 quad_perm:[1,0,3,2] row_mask:0xf bank_mask:0xf bound_ctrl:1
	ds_read_b128 v[68:71], v199 offset:27424
	v_add_f32_dpp v86, v86, v86 quad_perm:[2,3,0,1] row_mask:0xf bank_mask:0xf bound_ctrl:1
	v_add_f32_dpp v92, v92, v92 quad_perm:[2,3,0,1] row_mask:0xf bank_mask:0xf bound_ctrl:1
	ds_read_b128 v[72:75], v199 offset:27440
	v_add_f32_dpp v86, v86, v86 row_half_mirror row_mask:0xf bank_mask:0xf bound_ctrl:1
	v_add_f32_dpp v92, v92, v92 row_half_mirror row_mask:0xf bank_mask:0xf bound_ctrl:1
	v_pk_fma_f32 v[164:165], v[36:37], v[42:43], v[172:173] op_sel_hi:[1,0,1]
	v_pk_fma_f32 v[166:167], v[38:39], v[42:43], v[174:175] op_sel_hi:[1,0,1]
	v_pk_fma_f32 v[168:169], v[40:41], v[42:43], v[176:177] op_sel_hi:[1,0,1]
	s_waitcnt lgkmcnt(10)
	v_pk_fma_f32 v[94:95], v[26:27], v[86:87], v[162:163] op_sel_hi:[1,0,1]
	v_pk_fma_f32 v[96:97], v[28:29], v[86:87], v[164:165] op_sel_hi:[1,0,1]
	v_pk_fma_f32 v[98:99], v[30:31], v[86:87], v[166:167] op_sel_hi:[1,0,1]
	v_pk_fma_f32 v[100:101], v[32:33], v[86:87], v[168:169] op_sel_hi:[1,0,1]
	ds_write_b32 v201, v92 offset:3584
	v_pk_mul_f32 v[90:91], v[52:53], v[170:171]
	v_pk_fma_f32 v[90:91], v[54:55], v[172:173], v[90:91]
	v_pk_fma_f32 v[90:91], v[56:57], v[174:175], v[90:91]
	v_pk_fma_f32 v[90:91], v[58:59], v[176:177], v[90:91]
	ds_read_b128 v[52:55], v199 offset:26912
	v_add_f32_e32 v93, v90, v91
	ds_read_b128 v[56:59], v199 offset:26928
	s_waitcnt lgkmcnt(5)
	v_pk_mul_f32 v[88:89], v[44:45], v[94:95]
	ds_read_b128 v[2:5], v199 offset:28224
	v_pk_fma_f32 v[88:89], v[46:47], v[96:97], v[88:89]
	ds_read_b128 v[6:9], v199 offset:28240
	v_pk_fma_f32 v[88:89], v[48:49], v[98:99], v[88:89]
	ds_read_b128 v[34:37], v199 offset:29248
	v_pk_fma_f32 v[88:89], v[50:51], v[100:101], v[88:89]
	ds_read_b128 v[38:41], v199 offset:29264
	v_add_f32_e32 v86, v88, v89
	ds_read_b32 v42, v200 offset:28224
	v_pk_fma_f32 v[162:163], v[76:77], v[84:85], v[94:95] op_sel_hi:[1,0,1]
	v_add_f32_dpp v86, v86, v86 quad_perm:[1,0,3,2] row_mask:0xf bank_mask:0xf bound_ctrl:1
	v_add_f32_dpp v93, v93, v93 quad_perm:[1,0,3,2] row_mask:0xf bank_mask:0xf bound_ctrl:1
	ds_read_b128 v[26:29], v199 offset:28992
	v_add_f32_dpp v86, v86, v86 quad_perm:[2,3,0,1] row_mask:0xf bank_mask:0xf bound_ctrl:1
	v_add_f32_dpp v93, v93, v93 quad_perm:[2,3,0,1] row_mask:0xf bank_mask:0xf bound_ctrl:1
	ds_read_b128 v[30:33], v199 offset:29008
	v_add_f32_dpp v86, v86, v86 row_half_mirror row_mask:0xf bank_mask:0xf bound_ctrl:1
	v_add_f32_dpp v93, v93, v93 row_half_mirror row_mask:0xf bank_mask:0xf bound_ctrl:1
	v_pk_fma_f32 v[164:165], v[78:79], v[84:85], v[96:97] op_sel_hi:[1,0,1]
	v_pk_fma_f32 v[166:167], v[80:81], v[84:85], v[98:99] op_sel_hi:[1,0,1]
	v_pk_fma_f32 v[168:169], v[82:83], v[84:85], v[100:101] op_sel_hi:[1,0,1]
	s_waitcnt lgkmcnt(10)
	v_pk_fma_f32 v[170:171], v[68:69], v[86:87], v[162:163] op_sel_hi:[1,0,1]
	v_pk_fma_f32 v[172:173], v[70:71], v[86:87], v[164:165] op_sel_hi:[1,0,1]
	v_pk_fma_f32 v[174:175], v[72:73], v[86:87], v[166:167] op_sel_hi:[1,0,1]
	v_pk_fma_f32 v[176:177], v[74:75], v[86:87], v[168:169] op_sel_hi:[1,0,1]
	ds_write_b32 v201, v93 offset:3840
	v_pk_mul_f32 v[90:91], v[10:11], v[94:95]
	v_pk_fma_f32 v[90:91], v[12:13], v[96:97], v[90:91]
	v_pk_fma_f32 v[90:91], v[14:15], v[98:99], v[90:91]
	v_pk_fma_f32 v[90:91], v[16:17], v[100:101], v[90:91]
	ds_read_b128 v[10:13], v199 offset:28480
	v_add_f32_e32 v92, v90, v91
	ds_read_b128 v[14:17], v199 offset:28496
	s_waitcnt lgkmcnt(5)
	v_pk_mul_f32 v[88:89], v[2:3], v[170:171]
	ds_read_b128 v[44:47], v199 offset:29792
	v_pk_fma_f32 v[88:89], v[4:5], v[172:173], v[88:89]
	ds_read_b128 v[48:51], v199 offset:29808
	v_pk_fma_f32 v[88:89], v[6:7], v[174:175], v[88:89]
	ds_read_b128 v[76:79], v199 offset:30816
	v_pk_fma_f32 v[88:89], v[8:9], v[176:177], v[88:89]
	ds_read_b128 v[80:83], v199 offset:30832
	v_add_f32_e32 v86, v88, v89
	ds_read_b32 v84, v200 offset:29792
	v_pk_fma_f32 v[162:163], v[34:35], v[42:43], v[170:171] op_sel_hi:[1,0,1]
	v_add_f32_dpp v86, v86, v86 quad_perm:[1,0,3,2] row_mask:0xf bank_mask:0xf bound_ctrl:1
	v_add_f32_dpp v92, v92, v92 quad_perm:[1,0,3,2] row_mask:0xf bank_mask:0xf bound_ctrl:1
	ds_read_b128 v[68:71], v199 offset:30560
	v_add_f32_dpp v86, v86, v86 quad_perm:[2,3,0,1] row_mask:0xf bank_mask:0xf bound_ctrl:1
	v_add_f32_dpp v92, v92, v92 quad_perm:[2,3,0,1] row_mask:0xf bank_mask:0xf bound_ctrl:1
	ds_read_b128 v[72:75], v199 offset:30576
	v_add_f32_dpp v86, v86, v86 row_half_mirror row_mask:0xf bank_mask:0xf bound_ctrl:1
	v_add_f32_dpp v92, v92, v92 row_half_mirror row_mask:0xf bank_mask:0xf bound_ctrl:1
	v_pk_fma_f32 v[164:165], v[36:37], v[42:43], v[172:173] op_sel_hi:[1,0,1]
	v_pk_fma_f32 v[166:167], v[38:39], v[42:43], v[174:175] op_sel_hi:[1,0,1]
	v_pk_fma_f32 v[168:169], v[40:41], v[42:43], v[176:177] op_sel_hi:[1,0,1]
	s_waitcnt lgkmcnt(10)
; template <int CPL>
; DI void scan_block2(CP p, int layer, int s, int d, int hd, int rowhalf, char* smem) {
;     ...
;       for (int jj = 0; jj < nst; ++jj) {
;         float4 na[CPL / 4], ny[CPL / 4], nw[CPL / 4], nb[CPL / 4], nk[CPL / 4];
;         float nvv;
;         {
;           const int jn = jj + 1;
;           const float* o = ob + jn * 392 + cg * CPL;
; #pragma unroll
;           for (int i = 0; i < CPL / 4; ++i) {
;             na[i] = *(const float4*)(o + 4 * i); ny[i] = *(const float4*)(o + 64 + 4 * i); nw[i] = *(const float4*)(o + 128 + 4 * i);
;             nb[i] = *(const float4*)(o + 192 + 4 * i); nk[i] = *(const float4*)(o + 256 + 4 * i);
;           }
;           nvv = ob[jn * 392 + 320 + row];
;         }
;         f2 A[NV], Y[NV], W[NV], B[NV], K[NV];
; #pragma unroll
;         for (int i = 0; i < CPL / 4; ++i) {
;           A[2 * i] = mk2(ca[i].x, ca[i].y); A[2 * i + 1] = mk2(ca[i].z, ca[i].w);
;           Y[2 * i] = mk2(cy[i].x, cy[i].y); Y[2 * i + 1] = mk2(cy[i].z, cy[i].w);
;           W[2 * i] = mk2(cw[i].x, cw[i].y); W[2 * i + 1] = mk2(cw[i].z, cw[i].w);
;           B[2 * i] = mk2(cb[i].x, cb[i].y); B[2 * i + 1] = mk2(cb[i].z, cb[i].w);
;           K[2 * i] = mk2(ck[i].x, ck[i].y); K[2 * i + 1] = mk2(ck[i].z, ck[i].w);
;         }
;         const float vv = cvv;
;         f2 pa0 = S[0] * A[0], pa1 = S[1] * A[1];
; #pragma unroll
;         for (int i = 2; i < NV; i += 2) { pa0 = S[i] * A[i] + pa0; pa1 = S[i + 1] * A[i + 1] + pa1; }
;         pa0 = pa0 + pa1;
;         float da = pa0.x + pa0.y;
;         const f2 vvv = mk2(vv, vv);
;         f2 SW[NV];
; #pragma unroll
;         for (int i = 0; i < NV; ++i) SW[i] = S[i] * W[i] + vvv * K[i];
;         da += __int_as_float(__builtin_amdgcn_update_dpp(0, __float_as_int(da), 0xB1, 0xf, 0xf, false));
;         da += __int_as_float(__builtin_amdgcn_update_dpp(0, __float_as_int(da), 0x4E, 0xf, 0xf, false));
;         if (CPL == 8) da += __int_as_float(__builtin_amdgcn_update_dpp(0, __float_as_int(da), 0x141, 0xf, 0xf, false));
;         const f2 dav = mk2(da, da);
; #pragma unroll
;         for (int i = 0; i < NV; ++i) S[i] = dav * B[i] + SW[i];
;         f2 py0 = S[0] * Y[0], py1 = S[1] * Y[1];
; #pragma unroll
;         for (int i = 2; i < NV; i += 2) { py0 = S[i] * Y[i] + py0; py1 = S[i + 1] * Y[i + 1] + py1; }
;         py0 = py0 + py1;
;         float yv = py0.x + py0.y;
	v_pk_fma_f32 v[94:95], v[26:27], v[86:87], v[162:163] op_sel_hi:[1,0,1]
	v_pk_fma_f32 v[96:97], v[28:29], v[86:87], v[164:165] op_sel_hi:[1,0,1]
	v_pk_fma_f32 v[98:99], v[30:31], v[86:87], v[166:167] op_sel_hi:[1,0,1]
	v_pk_fma_f32 v[100:101], v[32:33], v[86:87], v[168:169] op_sel_hi:[1,0,1]
	ds_write_b32 v201, v92 offset:4096
	v_pk_mul_f32 v[90:91], v[52:53], v[170:171]
	v_pk_fma_f32 v[90:91], v[54:55], v[172:173], v[90:91]
	v_pk_fma_f32 v[90:91], v[56:57], v[174:175], v[90:91]
	v_pk_fma_f32 v[90:91], v[58:59], v[176:177], v[90:91]
	ds_read_b128 v[52:55], v199 offset:30048
	v_add_f32_e32 v93, v90, v91
	ds_read_b128 v[56:59], v199 offset:30064
	s_waitcnt lgkmcnt(5)
	v_pk_mul_f32 v[88:89], v[44:45], v[94:95]
	ds_read_b128 v[2:5], v199 offset:31360
	v_pk_fma_f32 v[88:89], v[46:47], v[96:97], v[88:89]
	ds_read_b128 v[6:9], v199 offset:31376
	v_pk_fma_f32 v[88:89], v[48:49], v[98:99], v[88:89]
	ds_read_b128 v[34:37], v199 offset:32384
	v_pk_fma_f32 v[88:89], v[50:51], v[100:101], v[88:89]
	ds_read_b128 v[38:41], v199 offset:32400
	v_add_f32_e32 v86, v88, v89
	ds_read_b32 v42, v200 offset:31360
	v_pk_fma_f32 v[162:163], v[76:77], v[84:85], v[94:95] op_sel_hi:[1,0,1]
	v_add_f32_dpp v86, v86, v86 quad_perm:[1,0,3,2] row_mask:0xf bank_mask:0xf bound_ctrl:1
	v_add_f32_dpp v93, v93, v93 quad_perm:[1,0,3,2] row_mask:0xf bank_mask:0xf bound_ctrl:1
	ds_read_b128 v[26:29], v199 offset:32128
	v_add_f32_dpp v86, v86, v86 quad_perm:[2,3,0,1] row_mask:0xf bank_mask:0xf bound_ctrl:1
	v_add_f32_dpp v93, v93, v93 quad_perm:[2,3,0,1] row_mask:0xf bank_mask:0xf bound_ctrl:1
	ds_read_b128 v[30:33], v199 offset:32144
	v_add_f32_dpp v86, v86, v86 row_half_mirror row_mask:0xf bank_mask:0xf bound_ctrl:1
	v_add_f32_dpp v93, v93, v93 row_half_mirror row_mask:0xf bank_mask:0xf bound_ctrl:1
	v_pk_fma_f32 v[164:165], v[78:79], v[84:85], v[96:97] op_sel_hi:[1,0,1]
	v_pk_fma_f32 v[166:167], v[80:81], v[84:85], v[98:99] op_sel_hi:[1,0,1]
	v_pk_fma_f32 v[168:169], v[82:83], v[84:85], v[100:101] op_sel_hi:[1,0,1]
	s_waitcnt lgkmcnt(10)
	v_pk_fma_f32 v[170:171], v[68:69], v[86:87], v[162:163] op_sel_hi:[1,0,1]
	v_pk_fma_f32 v[172:173], v[70:71], v[86:87], v[164:165] op_sel_hi:[1,0,1]
	v_pk_fma_f32 v[174:175], v[72:73], v[86:87], v[166:167] op_sel_hi:[1,0,1]
	v_pk_fma_f32 v[176:177], v[74:75], v[86:87], v[168:169] op_sel_hi:[1,0,1]
	ds_write_b32 v201, v93 offset:4352
	v_pk_mul_f32 v[90:91], v[10:11], v[94:95]
	v_pk_fma_f32 v[90:91], v[12:13], v[96:97], v[90:91]
	v_pk_fma_f32 v[90:91], v[14:15], v[98:99], v[90:91]
	v_pk_fma_f32 v[90:91], v[16:17], v[100:101], v[90:91]
	ds_read_b128 v[10:13], v199 offset:31616
	v_add_f32_e32 v92, v90, v91
	ds_read_b128 v[14:17], v199 offset:31632
	s_waitcnt lgkmcnt(5)
	v_pk_mul_f32 v[88:89], v[2:3], v[170:171]
	ds_read_b128 v[44:47], v199 offset:32928
	v_pk_fma_f32 v[88:89], v[4:5], v[172:173], v[88:89]
	ds_read_b128 v[48:51], v199 offset:32944
	v_pk_fma_f32 v[88:89], v[6:7], v[174:175], v[88:89]
	ds_read_b128 v[76:79], v199 offset:33952
	v_pk_fma_f32 v[88:89], v[8:9], v[176:177], v[88:89]
	ds_read_b128 v[80:83], v199 offset:33968
	v_add_f32_e32 v86, v88, v89
	ds_read_b32 v84, v200 offset:32928
	v_pk_fma_f32 v[162:163], v[34:35], v[42:43], v[170:171] op_sel_hi:[1,0,1]
	v_add_f32_dpp v86, v86, v86 quad_perm:[1,0,3,2] row_mask:0xf bank_mask:0xf bound_ctrl:1
	v_add_f32_dpp v92, v92, v92 quad_perm:[1,0,3,2] row_mask:0xf bank_mask:0xf bound_ctrl:1
	ds_read_b128 v[68:71], v199 offset:33696
	v_add_f32_dpp v86, v86, v86 quad_perm:[2,3,0,1] row_mask:0xf bank_mask:0xf bound_ctrl:1
	v_add_f32_dpp v92, v92, v92 quad_perm:[2,3,0,1] row_mask:0xf bank_mask:0xf bound_ctrl:1
	ds_read_b128 v[72:75], v199 offset:33712
	v_add_f32_dpp v86, v86, v86 row_half_mirror row_mask:0xf bank_mask:0xf bound_ctrl:1
	v_add_f32_dpp v92, v92, v92 row_half_mirror row_mask:0xf bank_mask:0xf bound_ctrl:1
	v_pk_fma_f32 v[164:165], v[36:37], v[42:43], v[172:173] op_sel_hi:[1,0,1]
	v_pk_fma_f32 v[166:167], v[38:39], v[42:43], v[174:175] op_sel_hi:[1,0,1]
	v_pk_fma_f32 v[168:169], v[40:41], v[42:43], v[176:177] op_sel_hi:[1,0,1]
	s_waitcnt lgkmcnt(10)
	v_pk_fma_f32 v[94:95], v[26:27], v[86:87], v[162:163] op_sel_hi:[1,0,1]
	v_pk_fma_f32 v[96:97], v[28:29], v[86:87], v[164:165] op_sel_hi:[1,0,1]
	v_pk_fma_f32 v[98:99], v[30:31], v[86:87], v[166:167] op_sel_hi:[1,0,1]
	v_pk_fma_f32 v[100:101], v[32:33], v[86:87], v[168:169] op_sel_hi:[1,0,1]
	ds_write_b32 v201, v92 offset:4608
	v_pk_mul_f32 v[90:91], v[52:53], v[170:171]
	v_pk_fma_f32 v[90:91], v[54:55], v[172:173], v[90:91]
	v_pk_fma_f32 v[90:91], v[56:57], v[174:175], v[90:91]
	v_pk_fma_f32 v[90:91], v[58:59], v[176:177], v[90:91]
	ds_read_b128 v[52:55], v199 offset:33184
	v_add_f32_e32 v93, v90, v91
	ds_read_b128 v[56:59], v199 offset:33200
	s_waitcnt lgkmcnt(5)
	v_pk_mul_f32 v[88:89], v[44:45], v[94:95]
	ds_read_b128 v[2:5], v199 offset:34496
	v_pk_fma_f32 v[88:89], v[46:47], v[96:97], v[88:89]
	ds_read_b128 v[6:9], v199 offset:34512
	v_pk_fma_f32 v[88:89], v[48:49], v[98:99], v[88:89]
	ds_read_b128 v[34:37], v199 offset:35520
	v_pk_fma_f32 v[88:89], v[50:51], v[100:101], v[88:89]
	ds_read_b128 v[38:41], v199 offset:35536
	v_add_f32_e32 v86, v88, v89
	ds_read_b32 v42, v200 offset:34496
	v_pk_fma_f32 v[162:163], v[76:77], v[84:85], v[94:95] op_sel_hi:[1,0,1]
	v_add_f32_dpp v86, v86, v86 quad_perm:[1,0,3,2] row_mask:0xf bank_mask:0xf bound_ctrl:1
	v_add_f32_dpp v93, v93, v93 quad_perm:[1,0,3,2] row_mask:0xf bank_mask:0xf bound_ctrl:1
	ds_read_b128 v[26:29], v199 offset:35264
	v_add_f32_dpp v86, v86, v86 quad_perm:[2,3,0,1] row_mask:0xf bank_mask:0xf bound_ctrl:1
	v_add_f32_dpp v93, v93, v93 quad_perm:[2,3,0,1] row_mask:0xf bank_mask:0xf bound_ctrl:1
	ds_read_b128 v[30:33], v199 offset:35280
	v_add_f32_dpp v86, v86, v86 row_half_mirror row_mask:0xf bank_mask:0xf bound_ctrl:1
	v_add_f32_dpp v93, v93, v93 row_half_mirror row_mask:0xf bank_mask:0xf bound_ctrl:1
	v_pk_fma_f32 v[164:165], v[78:79], v[84:85], v[96:97] op_sel_hi:[1,0,1]
	v_pk_fma_f32 v[166:167], v[80:81], v[84:85], v[98:99] op_sel_hi:[1,0,1]
	v_pk_fma_f32 v[168:169], v[82:83], v[84:85], v[100:101] op_sel_hi:[1,0,1]
	s_waitcnt lgkmcnt(10)
; template <int CPL>
; DI void scan_block2(CP p, int layer, int s, int d, int hd, int rowhalf, char* smem) {
;     ...
;       for (int jj = 0; jj < nst; ++jj) {
;         float4 na[CPL / 4], ny[CPL / 4], nw[CPL / 4], nb[CPL / 4], nk[CPL / 4];
;         float nvv;
;         {
;           const int jn = jj + 1;
;           const float* o = ob + jn * 392 + cg * CPL;
; #pragma unroll
;           for (int i = 0; i < CPL / 4; ++i) {
;             na[i] = *(const float4*)(o + 4 * i); ny[i] = *(const float4*)(o + 64 + 4 * i); nw[i] = *(const float4*)(o + 128 + 4 * i);
;             nb[i] = *(const float4*)(o + 192 + 4 * i); nk[i] = *(const float4*)(o + 256 + 4 * i);
;           }
;           nvv = ob[jn * 392 + 320 + row];
;         }
;         f2 A[NV], Y[NV], W[NV], B[NV], K[NV];
; #pragma unroll
;         for (int i = 0; i < CPL / 4; ++i) {
;           A[2 * i] = mk2(ca[i].x, ca[i].y); A[2 * i + 1] = mk2(ca[i].z, ca[i].w);
;           Y[2 * i] = mk2(cy[i].x, cy[i].y); Y[2 * i + 1] = mk2(cy[i].z, cy[i].w);
;           W[2 * i] = mk2(cw[i].x, cw[i].y); W[2 * i + 1] = mk2(cw[i].z, cw[i].w);
;           B[2 * i] = mk2(cb[i].x, cb[i].y); B[2 * i + 1] = mk2(cb[i].z, cb[i].w);
;           K[2 * i] = mk2(ck[i].x, ck[i].y); K[2 * i + 1] = mk2(ck[i].z, ck[i].w);
;         }
;         const float vv = cvv;
;         f2 pa0 = S[0] * A[0], pa1 = S[1] * A[1];
; #pragma unroll
;         for (int i = 2; i < NV; i += 2) { pa0 = S[i] * A[i] + pa0; pa1 = S[i + 1] * A[i + 1] + pa1; }
;         pa0 = pa0 + pa1;
;         float da = pa0.x + pa0.y;
;         const f2 vvv = mk2(vv, vv);
;         f2 SW[NV];
; #pragma unroll
;         for (int i = 0; i < NV; ++i) SW[i] = S[i] * W[i] + vvv * K[i];
;         da += __int_as_float(__builtin_amdgcn_update_dpp(0, __float_as_int(da), 0xB1, 0xf, 0xf, false));
;         da += __int_as_float(__builtin_amdgcn_update_dpp(0, __float_as_int(da), 0x4E, 0xf, 0xf, false));
;         if (CPL == 8) da += __int_as_float(__builtin_amdgcn_update_dpp(0, __float_as_int(da), 0x141, 0xf, 0xf, false));
;         const f2 dav = mk2(da, da);
; #pragma unroll
;         for (int i = 0; i < NV; ++i) S[i] = dav * B[i] + SW[i];
;         f2 py0 = S[0] * Y[0], py1 = S[1] * Y[1];
; #pragma unroll
;         for (int i = 2; i < NV; i += 2) { py0 = S[i] * Y[i] + py0; py1 = S[i + 1] * Y[i + 1] + py1; }
;         py0 = py0 + py1;
;         float yv = py0.x + py0.y;
	v_pk_fma_f32 v[170:171], v[68:69], v[86:87], v[162:163] op_sel_hi:[1,0,1]
	v_pk_fma_f32 v[172:173], v[70:71], v[86:87], v[164:165] op_sel_hi:[1,0,1]
	v_pk_fma_f32 v[174:175], v[72:73], v[86:87], v[166:167] op_sel_hi:[1,0,1]
	v_pk_fma_f32 v[176:177], v[74:75], v[86:87], v[168:169] op_sel_hi:[1,0,1]
	ds_write_b32 v201, v93 offset:4864
	v_pk_mul_f32 v[90:91], v[10:11], v[94:95]
	v_pk_fma_f32 v[90:91], v[12:13], v[96:97], v[90:91]
	v_pk_fma_f32 v[90:91], v[14:15], v[98:99], v[90:91]
	v_pk_fma_f32 v[90:91], v[16:17], v[100:101], v[90:91]
	ds_read_b128 v[10:13], v199 offset:34752
	v_add_f32_e32 v92, v90, v91
	ds_read_b128 v[14:17], v199 offset:34768
	s_waitcnt lgkmcnt(5)
	v_pk_mul_f32 v[88:89], v[2:3], v[170:171]
	ds_read_b128 v[44:47], v199 offset:36064
	v_pk_fma_f32 v[88:89], v[4:5], v[172:173], v[88:89]
	ds_read_b128 v[48:51], v199 offset:36080
	v_pk_fma_f32 v[88:89], v[6:7], v[174:175], v[88:89]
	ds_read_b128 v[76:79], v199 offset:37088
	v_pk_fma_f32 v[88:89], v[8:9], v[176:177], v[88:89]
	ds_read_b128 v[80:83], v199 offset:37104
	v_add_f32_e32 v86, v88, v89
	ds_read_b32 v84, v200 offset:36064
	v_pk_fma_f32 v[162:163], v[34:35], v[42:43], v[170:171] op_sel_hi:[1,0,1]
	v_add_f32_dpp v86, v86, v86 quad_perm:[1,0,3,2] row_mask:0xf bank_mask:0xf bound_ctrl:1
	v_add_f32_dpp v92, v92, v92 quad_perm:[1,0,3,2] row_mask:0xf bank_mask:0xf bound_ctrl:1
	ds_read_b128 v[68:71], v199 offset:36832
	v_add_f32_dpp v86, v86, v86 quad_perm:[2,3,0,1] row_mask:0xf bank_mask:0xf bound_ctrl:1
	v_add_f32_dpp v92, v92, v92 quad_perm:[2,3,0,1] row_mask:0xf bank_mask:0xf bound_ctrl:1
	ds_read_b128 v[72:75], v199 offset:36848
	v_add_f32_dpp v86, v86, v86 row_half_mirror row_mask:0xf bank_mask:0xf bound_ctrl:1
	v_add_f32_dpp v92, v92, v92 row_half_mirror row_mask:0xf bank_mask:0xf bound_ctrl:1
	v_pk_fma_f32 v[164:165], v[36:37], v[42:43], v[172:173] op_sel_hi:[1,0,1]
	v_pk_fma_f32 v[166:167], v[38:39], v[42:43], v[174:175] op_sel_hi:[1,0,1]
	v_pk_fma_f32 v[168:169], v[40:41], v[42:43], v[176:177] op_sel_hi:[1,0,1]
	s_waitcnt lgkmcnt(10)
	v_pk_fma_f32 v[94:95], v[26:27], v[86:87], v[162:163] op_sel_hi:[1,0,1]
	v_pk_fma_f32 v[96:97], v[28:29], v[86:87], v[164:165] op_sel_hi:[1,0,1]
	v_pk_fma_f32 v[98:99], v[30:31], v[86:87], v[166:167] op_sel_hi:[1,0,1]
	v_pk_fma_f32 v[100:101], v[32:33], v[86:87], v[168:169] op_sel_hi:[1,0,1]
	ds_write_b32 v201, v92 offset:5120
	v_pk_mul_f32 v[90:91], v[52:53], v[170:171]
	v_pk_fma_f32 v[90:91], v[54:55], v[172:173], v[90:91]
	v_pk_fma_f32 v[90:91], v[56:57], v[174:175], v[90:91]
	v_pk_fma_f32 v[90:91], v[58:59], v[176:177], v[90:91]
	ds_read_b128 v[52:55], v199 offset:36320
	v_add_f32_e32 v93, v90, v91
	ds_read_b128 v[56:59], v199 offset:36336
	s_waitcnt lgkmcnt(5)
	v_pk_mul_f32 v[88:89], v[44:45], v[94:95]
	ds_read_b128 v[2:5], v199 offset:37632
	v_pk_fma_f32 v[88:89], v[46:47], v[96:97], v[88:89]
	ds_read_b128 v[6:9], v199 offset:37648
	v_pk_fma_f32 v[88:89], v[48:49], v[98:99], v[88:89]
	ds_read_b128 v[34:37], v199 offset:38656
	v_pk_fma_f32 v[88:89], v[50:51], v[100:101], v[88:89]
	ds_read_b128 v[38:41], v199 offset:38672
	v_add_f32_e32 v86, v88, v89
	ds_read_b32 v42, v200 offset:37632
	ds_read_b128 v[18:21], v199 offset:36576
	ds_read_b128 v[22:25], v199 offset:36592
	v_add_f32_dpp v86, v86, v86 quad_perm:[1,0,3,2] row_mask:0xf bank_mask:0xf bound_ctrl:1
	v_add_f32_dpp v93, v93, v93 quad_perm:[1,0,3,2] row_mask:0xf bank_mask:0xf bound_ctrl:1
	ds_read_b128 v[26:29], v199 offset:38400
	v_add_f32_dpp v86, v86, v86 quad_perm:[2,3,0,1] row_mask:0xf bank_mask:0xf bound_ctrl:1
	v_add_f32_dpp v93, v93, v93 quad_perm:[2,3,0,1] row_mask:0xf bank_mask:0xf bound_ctrl:1
	ds_read_b128 v[30:33], v199 offset:38416
	v_add_f32_dpp v86, v86, v86 row_half_mirror row_mask:0xf bank_mask:0xf bound_ctrl:1
	v_add_f32_dpp v93, v93, v93 row_half_mirror row_mask:0xf bank_mask:0xf bound_ctrl:1
	v_pk_fma_f32 v[162:163], v[76:77], v[84:85], v[94:95] op_sel_hi:[1,0,1]
	v_pk_fma_f32 v[164:165], v[78:79], v[84:85], v[96:97] op_sel_hi:[1,0,1]
	v_pk_fma_f32 v[166:167], v[80:81], v[84:85], v[98:99] op_sel_hi:[1,0,1]
	v_pk_fma_f32 v[168:169], v[82:83], v[84:85], v[100:101] op_sel_hi:[1,0,1]
	s_waitcnt lgkmcnt(12)
	v_pk_fma_f32 v[170:171], v[68:69], v[86:87], v[162:163] op_sel_hi:[1,0,1]
	v_pk_fma_f32 v[172:173], v[70:71], v[86:87], v[164:165] op_sel_hi:[1,0,1]
	v_pk_fma_f32 v[174:175], v[72:73], v[86:87], v[166:167] op_sel_hi:[1,0,1]
	v_pk_fma_f32 v[176:177], v[74:75], v[86:87], v[168:169] op_sel_hi:[1,0,1]
	s_waitcnt lgkmcnt(2)
	v_pk_mul_f32 v[170:171], v[170:171], v[18:19]
	v_pk_mul_f32 v[172:173], v[172:173], v[20:21]
	v_pk_mul_f32 v[174:175], v[174:175], v[22:23]
	v_pk_mul_f32 v[176:177], v[176:177], v[24:25]
	ds_write_b32 v201, v93 offset:5376
	v_pk_mul_f32 v[90:91], v[10:11], v[94:95]
	v_pk_fma_f32 v[90:91], v[12:13], v[96:97], v[90:91]
	v_pk_fma_f32 v[90:91], v[14:15], v[98:99], v[90:91]
	v_pk_fma_f32 v[90:91], v[16:17], v[100:101], v[90:91]
	ds_read_b128 v[10:13], v199 offset:37888
	v_add_f32_e32 v92, v90, v91
	ds_read_b128 v[14:17], v199 offset:37904
	s_waitcnt lgkmcnt(7)
; template <int CPL>
; DI void scan_block2(CP p, int layer, int s, int d, int hd, int rowhalf, char* smem) {
;     ...
;       for (int jj = 0; jj < nst; ++jj) {
;         float4 na[CPL / 4], ny[CPL / 4], nw[CPL / 4], nb[CPL / 4], nk[CPL / 4];
;         float nvv;
;         {
;           const int jn = jj + 1;
;           const float* o = ob + jn * 392 + cg * CPL;
; #pragma unroll
;           for (int i = 0; i < CPL / 4; ++i) {
;             na[i] = *(const float4*)(o + 4 * i); ny[i] = *(const float4*)(o + 64 + 4 * i); nw[i] = *(const float4*)(o + 128 + 4 * i);
;             nb[i] = *(const float4*)(o + 192 + 4 * i); nk[i] = *(const float4*)(o + 256 + 4 * i);
;           }
;           nvv = ob[jn * 392 + 320 + row];
;         }
;         f2 A[NV], Y[NV], W[NV], B[NV], K[NV];
; #pragma unroll
;         for (int i = 0; i < CPL / 4; ++i) {
;           A[2 * i] = mk2(ca[i].x, ca[i].y); A[2 * i + 1] = mk2(ca[i].z, ca[i].w);
;           Y[2 * i] = mk2(cy[i].x, cy[i].y); Y[2 * i + 1] = mk2(cy[i].z, cy[i].w);
;           W[2 * i] = mk2(cw[i].x, cw[i].y); W[2 * i + 1] = mk2(cw[i].z, cw[i].w);
;           B[2 * i] = mk2(cb[i].x, cb[i].y); B[2 * i + 1] = mk2(cb[i].z, cb[i].w);
;           K[2 * i] = mk2(ck[i].x, ck[i].y); K[2 * i + 1] = mk2(ck[i].z, ck[i].w);
;         }
;         const float vv = cvv;
;         f2 pa0 = S[0] * A[0], pa1 = S[1] * A[1];
; #pragma unroll
;         for (int i = 2; i < NV; i += 2) { pa0 = S[i] * A[i] + pa0; pa1 = S[i + 1] * A[i + 1] + pa1; }
;         pa0 = pa0 + pa1;
;         float da = pa0.x + pa0.y;
;         const f2 vvv = mk2(vv, vv);
;         f2 SW[NV];
; #pragma unroll
;         for (int i = 0; i < NV; ++i) SW[i] = S[i] * W[i] + vvv * K[i];
;         da += __int_as_float(__builtin_amdgcn_update_dpp(0, __float_as_int(da), 0xB1, 0xf, 0xf, false));
;         da += __int_as_float(__builtin_amdgcn_update_dpp(0, __float_as_int(da), 0x4E, 0xf, 0xf, false));
;         if (CPL == 8) da += __int_as_float(__builtin_amdgcn_update_dpp(0, __float_as_int(da), 0x141, 0xf, 0xf, false));
;         const f2 dav = mk2(da, da);
; #pragma unroll
;         for (int i = 0; i < NV; ++i) S[i] = dav * B[i] + SW[i];
;         f2 py0 = S[0] * Y[0], py1 = S[1] * Y[1];
; #pragma unroll
;         for (int i = 2; i < NV; i += 2) { py0 = S[i] * Y[i] + py0; py1 = S[i + 1] * Y[i + 1] + py1; }
;         py0 = py0 + py1;
;         float yv = py0.x + py0.y;
	v_pk_mul_f32 v[88:89], v[2:3], v[170:171]
	ds_read_b128 v[44:47], v199 offset:39200
	v_pk_fma_f32 v[88:89], v[4:5], v[172:173], v[88:89]
	ds_read_b128 v[48:51], v199 offset:39216
	v_pk_fma_f32 v[88:89], v[6:7], v[174:175], v[88:89]
	ds_read_b128 v[76:79], v199 offset:40224
	v_pk_fma_f32 v[88:89], v[8:9], v[176:177], v[88:89]
	ds_read_b128 v[80:83], v199 offset:40240
	v_add_f32_e32 v86, v88, v89
	ds_read_b32 v84, v200 offset:39200
	v_pk_fma_f32 v[162:163], v[34:35], v[42:43], v[170:171] op_sel_hi:[1,0,1]
	v_add_f32_dpp v86, v86, v86 quad_perm:[1,0,3,2] row_mask:0xf bank_mask:0xf bound_ctrl:1
	v_add_f32_dpp v92, v92, v92 quad_perm:[1,0,3,2] row_mask:0xf bank_mask:0xf bound_ctrl:1
	ds_read_b128 v[68:71], v199 offset:39968
	v_add_f32_dpp v86, v86, v86 quad_perm:[2,3,0,1] row_mask:0xf bank_mask:0xf bound_ctrl:1
	v_add_f32_dpp v92, v92, v92 quad_perm:[2,3,0,1] row_mask:0xf bank_mask:0xf bound_ctrl:1
	ds_read_b128 v[72:75], v199 offset:39984
	v_add_f32_dpp v86, v86, v86 row_half_mirror row_mask:0xf bank_mask:0xf bound_ctrl:1
	v_add_f32_dpp v92, v92, v92 row_half_mirror row_mask:0xf bank_mask:0xf bound_ctrl:1
	v_pk_fma_f32 v[164:165], v[36:37], v[42:43], v[172:173] op_sel_hi:[1,0,1]
	v_pk_fma_f32 v[166:167], v[38:39], v[42:43], v[174:175] op_sel_hi:[1,0,1]
	v_pk_fma_f32 v[168:169], v[40:41], v[42:43], v[176:177] op_sel_hi:[1,0,1]
	s_waitcnt lgkmcnt(10)
	v_pk_fma_f32 v[94:95], v[26:27], v[86:87], v[162:163] op_sel_hi:[1,0,1]
	v_pk_fma_f32 v[96:97], v[28:29], v[86:87], v[164:165] op_sel_hi:[1,0,1]
	v_pk_fma_f32 v[98:99], v[30:31], v[86:87], v[166:167] op_sel_hi:[1,0,1]
	v_pk_fma_f32 v[100:101], v[32:33], v[86:87], v[168:169] op_sel_hi:[1,0,1]
	ds_write_b32 v201, v92 offset:5632
	v_pk_mul_f32 v[90:91], v[52:53], v[170:171]
	v_pk_fma_f32 v[90:91], v[54:55], v[172:173], v[90:91]
	v_pk_fma_f32 v[90:91], v[56:57], v[174:175], v[90:91]
	v_pk_fma_f32 v[90:91], v[58:59], v[176:177], v[90:91]
	ds_read_b128 v[52:55], v199 offset:39456
	v_add_f32_e32 v93, v90, v91
	ds_read_b128 v[56:59], v199 offset:39472
	s_waitcnt lgkmcnt(5)
	v_pk_mul_f32 v[88:89], v[44:45], v[94:95]
	ds_read_b128 v[2:5], v199 offset:40768
	v_pk_fma_f32 v[88:89], v[46:47], v[96:97], v[88:89]
	ds_read_b128 v[6:9], v199 offset:40784
	v_pk_fma_f32 v[88:89], v[48:49], v[98:99], v[88:89]
	ds_read_b128 v[34:37], v199 offset:41792
	v_pk_fma_f32 v[88:89], v[50:51], v[100:101], v[88:89]
	ds_read_b128 v[38:41], v199 offset:41808
	v_add_f32_e32 v86, v88, v89
	ds_read_b32 v42, v200 offset:40768
	v_pk_fma_f32 v[162:163], v[76:77], v[84:85], v[94:95] op_sel_hi:[1,0,1]
	v_add_f32_dpp v86, v86, v86 quad_perm:[1,0,3,2] row_mask:0xf bank_mask:0xf bound_ctrl:1
	v_add_f32_dpp v93, v93, v93 quad_perm:[1,0,3,2] row_mask:0xf bank_mask:0xf bound_ctrl:1
	ds_read_b128 v[26:29], v199 offset:41536
	v_add_f32_dpp v86, v86, v86 quad_perm:[2,3,0,1] row_mask:0xf bank_mask:0xf bound_ctrl:1
	v_add_f32_dpp v93, v93, v93 quad_perm:[2,3,0,1] row_mask:0xf bank_mask:0xf bound_ctrl:1
	ds_read_b128 v[30:33], v199 offset:41552
	v_add_f32_dpp v86, v86, v86 row_half_mirror row_mask:0xf bank_mask:0xf bound_ctrl:1
	v_add_f32_dpp v93, v93, v93 row_half_mirror row_mask:0xf bank_mask:0xf bound_ctrl:1
	v_pk_fma_f32 v[164:165], v[78:79], v[84:85], v[96:97] op_sel_hi:[1,0,1]
	v_pk_fma_f32 v[166:167], v[80:81], v[84:85], v[98:99] op_sel_hi:[1,0,1]
	v_pk_fma_f32 v[168:169], v[82:83], v[84:85], v[100:101] op_sel_hi:[1,0,1]
	s_waitcnt lgkmcnt(10)
	v_pk_fma_f32 v[170:171], v[68:69], v[86:87], v[162:163] op_sel_hi:[1,0,1]
	v_pk_fma_f32 v[172:173], v[70:71], v[86:87], v[164:165] op_sel_hi:[1,0,1]
	v_pk_fma_f32 v[174:175], v[72:73], v[86:87], v[166:167] op_sel_hi:[1,0,1]
	v_pk_fma_f32 v[176:177], v[74:75], v[86:87], v[168:169] op_sel_hi:[1,0,1]
	ds_write_b32 v201, v93 offset:5888
	v_pk_mul_f32 v[90:91], v[10:11], v[94:95]
	v_pk_fma_f32 v[90:91], v[12:13], v[96:97], v[90:91]
	v_pk_fma_f32 v[90:91], v[14:15], v[98:99], v[90:91]
	v_pk_fma_f32 v[90:91], v[16:17], v[100:101], v[90:91]
	ds_read_b128 v[10:13], v199 offset:41024
	v_add_f32_e32 v92, v90, v91
	ds_read_b128 v[14:17], v199 offset:41040
	s_waitcnt lgkmcnt(5)
	v_pk_mul_f32 v[88:89], v[2:3], v[170:171]
	ds_read_b128 v[44:47], v199 offset:42336
	v_pk_fma_f32 v[88:89], v[4:5], v[172:173], v[88:89]
	ds_read_b128 v[48:51], v199 offset:42352
	v_pk_fma_f32 v[88:89], v[6:7], v[174:175], v[88:89]
	ds_read_b128 v[76:79], v199 offset:43360
	v_pk_fma_f32 v[88:89], v[8:9], v[176:177], v[88:89]
	ds_read_b128 v[80:83], v199 offset:43376
	v_add_f32_e32 v86, v88, v89
	ds_read_b32 v84, v200 offset:42336
	v_pk_fma_f32 v[162:163], v[34:35], v[42:43], v[170:171] op_sel_hi:[1,0,1]
	v_add_f32_dpp v86, v86, v86 quad_perm:[1,0,3,2] row_mask:0xf bank_mask:0xf bound_ctrl:1
	v_add_f32_dpp v92, v92, v92 quad_perm:[1,0,3,2] row_mask:0xf bank_mask:0xf bound_ctrl:1
	ds_read_b128 v[68:71], v199 offset:43104
	v_add_f32_dpp v86, v86, v86 quad_perm:[2,3,0,1] row_mask:0xf bank_mask:0xf bound_ctrl:1
	v_add_f32_dpp v92, v92, v92 quad_perm:[2,3,0,1] row_mask:0xf bank_mask:0xf bound_ctrl:1
	ds_read_b128 v[72:75], v199 offset:43120
	v_add_f32_dpp v86, v86, v86 row_half_mirror row_mask:0xf bank_mask:0xf bound_ctrl:1
	v_add_f32_dpp v92, v92, v92 row_half_mirror row_mask:0xf bank_mask:0xf bound_ctrl:1
	v_pk_fma_f32 v[164:165], v[36:37], v[42:43], v[172:173] op_sel_hi:[1,0,1]
	v_pk_fma_f32 v[166:167], v[38:39], v[42:43], v[174:175] op_sel_hi:[1,0,1]
	v_pk_fma_f32 v[168:169], v[40:41], v[42:43], v[176:177] op_sel_hi:[1,0,1]
	s_waitcnt lgkmcnt(10)
; template <int CPL>
; DI void scan_block2(CP p, int layer, int s, int d, int hd, int rowhalf, char* smem) {
;     ...
;       for (int jj = 0; jj < nst; ++jj) {
;         float4 na[CPL / 4], ny[CPL / 4], nw[CPL / 4], nb[CPL / 4], nk[CPL / 4];
;         float nvv;
;         {
;           const int jn = jj + 1;
;           const float* o = ob + jn * 392 + cg * CPL;
; #pragma unroll
;           for (int i = 0; i < CPL / 4; ++i) {
;             na[i] = *(const float4*)(o + 4 * i); ny[i] = *(const float4*)(o + 64 + 4 * i); nw[i] = *(const float4*)(o + 128 + 4 * i);
;             nb[i] = *(const float4*)(o + 192 + 4 * i); nk[i] = *(const float4*)(o + 256 + 4 * i);
;           }
;           nvv = ob[jn * 392 + 320 + row];
;         }
;         f2 A[NV], Y[NV], W[NV], B[NV], K[NV];
; #pragma unroll
;         for (int i = 0; i < CPL / 4; ++i) {
;           A[2 * i] = mk2(ca[i].x, ca[i].y); A[2 * i + 1] = mk2(ca[i].z, ca[i].w);
;           Y[2 * i] = mk2(cy[i].x, cy[i].y); Y[2 * i + 1] = mk2(cy[i].z, cy[i].w);
;           W[2 * i] = mk2(cw[i].x, cw[i].y); W[2 * i + 1] = mk2(cw[i].z, cw[i].w);
;           B[2 * i] = mk2(cb[i].x, cb[i].y); B[2 * i + 1] = mk2(cb[i].z, cb[i].w);
;           K[2 * i] = mk2(ck[i].x, ck[i].y); K[2 * i + 1] = mk2(ck[i].z, ck[i].w);
;         }
;         const float vv = cvv;
;         f2 pa0 = S[0] * A[0], pa1 = S[1] * A[1];
; #pragma unroll
;         for (int i = 2; i < NV; i += 2) { pa0 = S[i] * A[i] + pa0; pa1 = S[i + 1] * A[i + 1] + pa1; }
;         pa0 = pa0 + pa1;
;         float da = pa0.x + pa0.y;
;         const f2 vvv = mk2(vv, vv);
;         f2 SW[NV];
; #pragma unroll
;         for (int i = 0; i < NV; ++i) SW[i] = S[i] * W[i] + vvv * K[i];
;         da += __int_as_float(__builtin_amdgcn_update_dpp(0, __float_as_int(da), 0xB1, 0xf, 0xf, false));
;         da += __int_as_float(__builtin_amdgcn_update_dpp(0, __float_as_int(da), 0x4E, 0xf, 0xf, false));
;         if (CPL == 8) da += __int_as_float(__builtin_amdgcn_update_dpp(0, __float_as_int(da), 0x141, 0xf, 0xf, false));
;         const f2 dav = mk2(da, da);
; #pragma unroll
;         for (int i = 0; i < NV; ++i) S[i] = dav * B[i] + SW[i];
;         f2 py0 = S[0] * Y[0], py1 = S[1] * Y[1];
; #pragma unroll
;         for (int i = 2; i < NV; i += 2) { py0 = S[i] * Y[i] + py0; py1 = S[i + 1] * Y[i + 1] + py1; }
;         py0 = py0 + py1;
;         float yv = py0.x + py0.y;
	v_pk_fma_f32 v[94:95], v[26:27], v[86:87], v[162:163] op_sel_hi:[1,0,1]
	v_pk_fma_f32 v[96:97], v[28:29], v[86:87], v[164:165] op_sel_hi:[1,0,1]
	v_pk_fma_f32 v[98:99], v[30:31], v[86:87], v[166:167] op_sel_hi:[1,0,1]
	v_pk_fma_f32 v[100:101], v[32:33], v[86:87], v[168:169] op_sel_hi:[1,0,1]
	ds_write_b32 v201, v92 offset:6144
	v_pk_mul_f32 v[90:91], v[52:53], v[170:171]
	v_pk_fma_f32 v[90:91], v[54:55], v[172:173], v[90:91]
	v_pk_fma_f32 v[90:91], v[56:57], v[174:175], v[90:91]
	v_pk_fma_f32 v[90:91], v[58:59], v[176:177], v[90:91]
	ds_read_b128 v[52:55], v199 offset:42592
	v_add_f32_e32 v93, v90, v91
	ds_read_b128 v[56:59], v199 offset:42608
	s_waitcnt lgkmcnt(5)
	v_pk_mul_f32 v[88:89], v[44:45], v[94:95]
	ds_read_b128 v[2:5], v199 offset:43904
	v_pk_fma_f32 v[88:89], v[46:47], v[96:97], v[88:89]
	ds_read_b128 v[6:9], v199 offset:43920
	v_pk_fma_f32 v[88:89], v[48:49], v[98:99], v[88:89]
	ds_read_b128 v[34:37], v199 offset:44928
	v_pk_fma_f32 v[88:89], v[50:51], v[100:101], v[88:89]
	ds_read_b128 v[38:41], v199 offset:44944
	v_add_f32_e32 v86, v88, v89
	ds_read_b32 v42, v200 offset:43904
	v_pk_fma_f32 v[162:163], v[76:77], v[84:85], v[94:95] op_sel_hi:[1,0,1]
	v_add_f32_dpp v86, v86, v86 quad_perm:[1,0,3,2] row_mask:0xf bank_mask:0xf bound_ctrl:1
	v_add_f32_dpp v93, v93, v93 quad_perm:[1,0,3,2] row_mask:0xf bank_mask:0xf bound_ctrl:1
	ds_read_b128 v[26:29], v199 offset:44672
	v_add_f32_dpp v86, v86, v86 quad_perm:[2,3,0,1] row_mask:0xf bank_mask:0xf bound_ctrl:1
	v_add_f32_dpp v93, v93, v93 quad_perm:[2,3,0,1] row_mask:0xf bank_mask:0xf bound_ctrl:1
	ds_read_b128 v[30:33], v199 offset:44688
	v_add_f32_dpp v86, v86, v86 row_half_mirror row_mask:0xf bank_mask:0xf bound_ctrl:1
	v_add_f32_dpp v93, v93, v93 row_half_mirror row_mask:0xf bank_mask:0xf bound_ctrl:1
	v_pk_fma_f32 v[164:165], v[78:79], v[84:85], v[96:97] op_sel_hi:[1,0,1]
	v_pk_fma_f32 v[166:167], v[80:81], v[84:85], v[98:99] op_sel_hi:[1,0,1]
	v_pk_fma_f32 v[168:169], v[82:83], v[84:85], v[100:101] op_sel_hi:[1,0,1]
	s_waitcnt lgkmcnt(10)
	v_pk_fma_f32 v[170:171], v[68:69], v[86:87], v[162:163] op_sel_hi:[1,0,1]
	v_pk_fma_f32 v[172:173], v[70:71], v[86:87], v[164:165] op_sel_hi:[1,0,1]
	v_pk_fma_f32 v[174:175], v[72:73], v[86:87], v[166:167] op_sel_hi:[1,0,1]
	v_pk_fma_f32 v[176:177], v[74:75], v[86:87], v[168:169] op_sel_hi:[1,0,1]
	ds_write_b32 v201, v93 offset:6400
	v_pk_mul_f32 v[90:91], v[10:11], v[94:95]
	v_pk_fma_f32 v[90:91], v[12:13], v[96:97], v[90:91]
	v_pk_fma_f32 v[90:91], v[14:15], v[98:99], v[90:91]
	v_pk_fma_f32 v[90:91], v[16:17], v[100:101], v[90:91]
	ds_read_b128 v[10:13], v199 offset:44160
	v_add_f32_e32 v92, v90, v91
	ds_read_b128 v[14:17], v199 offset:44176
	s_waitcnt lgkmcnt(5)
	v_pk_mul_f32 v[88:89], v[2:3], v[170:171]
	ds_read_b128 v[44:47], v199 offset:45472
	v_pk_fma_f32 v[88:89], v[4:5], v[172:173], v[88:89]
	ds_read_b128 v[48:51], v199 offset:45488
	v_pk_fma_f32 v[88:89], v[6:7], v[174:175], v[88:89]
	ds_read_b128 v[76:79], v199 offset:46496
	v_pk_fma_f32 v[88:89], v[8:9], v[176:177], v[88:89]
	ds_read_b128 v[80:83], v199 offset:46512
	v_add_f32_e32 v86, v88, v89
	ds_read_b32 v84, v200 offset:45472
	v_pk_fma_f32 v[162:163], v[34:35], v[42:43], v[170:171] op_sel_hi:[1,0,1]
	v_add_f32_dpp v86, v86, v86 quad_perm:[1,0,3,2] row_mask:0xf bank_mask:0xf bound_ctrl:1
	v_add_f32_dpp v92, v92, v92 quad_perm:[1,0,3,2] row_mask:0xf bank_mask:0xf bound_ctrl:1
	ds_read_b128 v[68:71], v199 offset:46240
	v_add_f32_dpp v86, v86, v86 quad_perm:[2,3,0,1] row_mask:0xf bank_mask:0xf bound_ctrl:1
	v_add_f32_dpp v92, v92, v92 quad_perm:[2,3,0,1] row_mask:0xf bank_mask:0xf bound_ctrl:1
	ds_read_b128 v[72:75], v199 offset:46256
	v_add_f32_dpp v86, v86, v86 row_half_mirror row_mask:0xf bank_mask:0xf bound_ctrl:1
	v_add_f32_dpp v92, v92, v92 row_half_mirror row_mask:0xf bank_mask:0xf bound_ctrl:1
	v_pk_fma_f32 v[164:165], v[36:37], v[42:43], v[172:173] op_sel_hi:[1,0,1]
	v_pk_fma_f32 v[166:167], v[38:39], v[42:43], v[174:175] op_sel_hi:[1,0,1]
	v_pk_fma_f32 v[168:169], v[40:41], v[42:43], v[176:177] op_sel_hi:[1,0,1]
	s_waitcnt lgkmcnt(10)
	v_pk_fma_f32 v[94:95], v[26:27], v[86:87], v[162:163] op_sel_hi:[1,0,1]
	v_pk_fma_f32 v[96:97], v[28:29], v[86:87], v[164:165] op_sel_hi:[1,0,1]
	v_pk_fma_f32 v[98:99], v[30:31], v[86:87], v[166:167] op_sel_hi:[1,0,1]
	v_pk_fma_f32 v[100:101], v[32:33], v[86:87], v[168:169] op_sel_hi:[1,0,1]
	ds_write_b32 v201, v92 offset:6656
	v_pk_mul_f32 v[90:91], v[52:53], v[170:171]
	v_pk_fma_f32 v[90:91], v[54:55], v[172:173], v[90:91]
	v_pk_fma_f32 v[90:91], v[56:57], v[174:175], v[90:91]
	v_pk_fma_f32 v[90:91], v[58:59], v[176:177], v[90:91]
	ds_read_b128 v[52:55], v199 offset:45728
	v_add_f32_e32 v93, v90, v91
	ds_read_b128 v[56:59], v199 offset:45744
	s_waitcnt lgkmcnt(5)
	v_pk_mul_f32 v[88:89], v[44:45], v[94:95]
	ds_read_b128 v[2:5], v199 offset:47040
	v_pk_fma_f32 v[88:89], v[46:47], v[96:97], v[88:89]
	ds_read_b128 v[6:9], v199 offset:47056
	v_pk_fma_f32 v[88:89], v[48:49], v[98:99], v[88:89]
	ds_read_b128 v[34:37], v199 offset:48064
	v_pk_fma_f32 v[88:89], v[50:51], v[100:101], v[88:89]
	ds_read_b128 v[38:41], v199 offset:48080
	v_add_f32_e32 v86, v88, v89
	ds_read_b32 v42, v200 offset:47040
	v_pk_fma_f32 v[162:163], v[76:77], v[84:85], v[94:95] op_sel_hi:[1,0,1]
	v_add_f32_dpp v86, v86, v86 quad_perm:[1,0,3,2] row_mask:0xf bank_mask:0xf bound_ctrl:1
	v_add_f32_dpp v93, v93, v93 quad_perm:[1,0,3,2] row_mask:0xf bank_mask:0xf bound_ctrl:1
	ds_read_b128 v[26:29], v199 offset:47808
	v_add_f32_dpp v86, v86, v86 quad_perm:[2,3,0,1] row_mask:0xf bank_mask:0xf bound_ctrl:1
	v_add_f32_dpp v93, v93, v93 quad_perm:[2,3,0,1] row_mask:0xf bank_mask:0xf bound_ctrl:1
	ds_read_b128 v[30:33], v199 offset:47824
	v_add_f32_dpp v86, v86, v86 row_half_mirror row_mask:0xf bank_mask:0xf bound_ctrl:1
	v_add_f32_dpp v93, v93, v93 row_half_mirror row_mask:0xf bank_mask:0xf bound_ctrl:1
	v_pk_fma_f32 v[164:165], v[78:79], v[84:85], v[96:97] op_sel_hi:[1,0,1]
	v_pk_fma_f32 v[166:167], v[80:81], v[84:85], v[98:99] op_sel_hi:[1,0,1]
	v_pk_fma_f32 v[168:169], v[82:83], v[84:85], v[100:101] op_sel_hi:[1,0,1]
	s_waitcnt lgkmcnt(10)
; template <int CPL>
; DI void scan_block2(CP p, int layer, int s, int d, int hd, int rowhalf, char* smem) {
;     ...
;       for (int jj = 0; jj < nst; ++jj) {
;         float4 na[CPL / 4], ny[CPL / 4], nw[CPL / 4], nb[CPL / 4], nk[CPL / 4];
;         float nvv;
;         {
;           const int jn = jj + 1;
;           const float* o = ob + jn * 392 + cg * CPL;
; #pragma unroll
;           for (int i = 0; i < CPL / 4; ++i) {
;             na[i] = *(const float4*)(o + 4 * i); ny[i] = *(const float4*)(o + 64 + 4 * i); nw[i] = *(const float4*)(o + 128 + 4 * i);
;             nb[i] = *(const float4*)(o + 192 + 4 * i); nk[i] = *(const float4*)(o + 256 + 4 * i);
;           }
;           nvv = ob[jn * 392 + 320 + row];
;         }
;         f2 A[NV], Y[NV], W[NV], B[NV], K[NV];
; #pragma unroll
;         for (int i = 0; i < CPL / 4; ++i) {
;           A[2 * i] = mk2(ca[i].x, ca[i].y); A[2 * i + 1] = mk2(ca[i].z, ca[i].w);
;           Y[2 * i] = mk2(cy[i].x, cy[i].y); Y[2 * i + 1] = mk2(cy[i].z, cy[i].w);
;           W[2 * i] = mk2(cw[i].x, cw[i].y); W[2 * i + 1] = mk2(cw[i].z, cw[i].w);
;           B[2 * i] = mk2(cb[i].x, cb[i].y); B[2 * i + 1] = mk2(cb[i].z, cb[i].w);
;           K[2 * i] = mk2(ck[i].x, ck[i].y); K[2 * i + 1] = mk2(ck[i].z, ck[i].w);
;         }
;         const float vv = cvv;
;         f2 pa0 = S[0] * A[0], pa1 = S[1] * A[1];
; #pragma unroll
;         for (int i = 2; i < NV; i += 2) { pa0 = S[i] * A[i] + pa0; pa1 = S[i + 1] * A[i + 1] + pa1; }
;         pa0 = pa0 + pa1;
;         float da = pa0.x + pa0.y;
;         const f2 vvv = mk2(vv, vv);
;         f2 SW[NV];
; #pragma unroll
;         for (int i = 0; i < NV; ++i) SW[i] = S[i] * W[i] + vvv * K[i];
;         da += __int_as_float(__builtin_amdgcn_update_dpp(0, __float_as_int(da), 0xB1, 0xf, 0xf, false));
;         da += __int_as_float(__builtin_amdgcn_update_dpp(0, __float_as_int(da), 0x4E, 0xf, 0xf, false));
;         if (CPL == 8) da += __int_as_float(__builtin_amdgcn_update_dpp(0, __float_as_int(da), 0x141, 0xf, 0xf, false));
;         const f2 dav = mk2(da, da);
; #pragma unroll
;         for (int i = 0; i < NV; ++i) S[i] = dav * B[i] + SW[i];
;         f2 py0 = S[0] * Y[0], py1 = S[1] * Y[1];
; #pragma unroll
;         for (int i = 2; i < NV; i += 2) { py0 = S[i] * Y[i] + py0; py1 = S[i + 1] * Y[i + 1] + py1; }
;         py0 = py0 + py1;
;         float yv = py0.x + py0.y;
	v_pk_fma_f32 v[170:171], v[68:69], v[86:87], v[162:163] op_sel_hi:[1,0,1]
	v_pk_fma_f32 v[172:173], v[70:71], v[86:87], v[164:165] op_sel_hi:[1,0,1]
	v_pk_fma_f32 v[174:175], v[72:73], v[86:87], v[166:167] op_sel_hi:[1,0,1]
	v_pk_fma_f32 v[176:177], v[74:75], v[86:87], v[168:169] op_sel_hi:[1,0,1]
	ds_write_b32 v201, v93 offset:6912
	v_pk_mul_f32 v[90:91], v[10:11], v[94:95]
	v_pk_fma_f32 v[90:91], v[12:13], v[96:97], v[90:91]
	v_pk_fma_f32 v[90:91], v[14:15], v[98:99], v[90:91]
	v_pk_fma_f32 v[90:91], v[16:17], v[100:101], v[90:91]
	ds_read_b128 v[10:13], v199 offset:47296
	v_add_f32_e32 v92, v90, v91
	ds_read_b128 v[14:17], v199 offset:47312
	s_waitcnt lgkmcnt(5)
	v_pk_mul_f32 v[88:89], v[2:3], v[170:171]
	ds_read_b128 v[44:47], v199 offset:48608
	v_pk_fma_f32 v[88:89], v[4:5], v[172:173], v[88:89]
	ds_read_b128 v[48:51], v199 offset:48624
	v_pk_fma_f32 v[88:89], v[6:7], v[174:175], v[88:89]
	ds_read_b128 v[76:79], v199 offset:49632
	v_pk_fma_f32 v[88:89], v[8:9], v[176:177], v[88:89]
	ds_read_b128 v[80:83], v199 offset:49648
	v_add_f32_e32 v86, v88, v89
	ds_read_b32 v84, v200 offset:48608
	v_pk_fma_f32 v[162:163], v[34:35], v[42:43], v[170:171] op_sel_hi:[1,0,1]
	v_add_f32_dpp v86, v86, v86 quad_perm:[1,0,3,2] row_mask:0xf bank_mask:0xf bound_ctrl:1
	v_add_f32_dpp v92, v92, v92 quad_perm:[1,0,3,2] row_mask:0xf bank_mask:0xf bound_ctrl:1
	ds_read_b128 v[68:71], v199 offset:49376
	v_add_f32_dpp v86, v86, v86 quad_perm:[2,3,0,1] row_mask:0xf bank_mask:0xf bound_ctrl:1
	v_add_f32_dpp v92, v92, v92 quad_perm:[2,3,0,1] row_mask:0xf bank_mask:0xf bound_ctrl:1
	ds_read_b128 v[72:75], v199 offset:49392
	v_add_f32_dpp v86, v86, v86 row_half_mirror row_mask:0xf bank_mask:0xf bound_ctrl:1
	v_add_f32_dpp v92, v92, v92 row_half_mirror row_mask:0xf bank_mask:0xf bound_ctrl:1
	v_pk_fma_f32 v[164:165], v[36:37], v[42:43], v[172:173] op_sel_hi:[1,0,1]
	v_pk_fma_f32 v[166:167], v[38:39], v[42:43], v[174:175] op_sel_hi:[1,0,1]
	v_pk_fma_f32 v[168:169], v[40:41], v[42:43], v[176:177] op_sel_hi:[1,0,1]
	s_waitcnt lgkmcnt(10)
	v_pk_fma_f32 v[94:95], v[26:27], v[86:87], v[162:163] op_sel_hi:[1,0,1]
	v_pk_fma_f32 v[96:97], v[28:29], v[86:87], v[164:165] op_sel_hi:[1,0,1]
	v_pk_fma_f32 v[98:99], v[30:31], v[86:87], v[166:167] op_sel_hi:[1,0,1]
	v_pk_fma_f32 v[100:101], v[32:33], v[86:87], v[168:169] op_sel_hi:[1,0,1]
	ds_write_b32 v201, v92 offset:7168
	v_pk_mul_f32 v[90:91], v[52:53], v[170:171]
	v_pk_fma_f32 v[90:91], v[54:55], v[172:173], v[90:91]
	v_pk_fma_f32 v[90:91], v[56:57], v[174:175], v[90:91]
	v_pk_fma_f32 v[90:91], v[58:59], v[176:177], v[90:91]
	ds_read_b128 v[52:55], v199 offset:48864
	v_add_f32_e32 v93, v90, v91
	ds_read_b128 v[56:59], v199 offset:48880
	s_waitcnt lgkmcnt(5)
	v_pk_mul_f32 v[88:89], v[44:45], v[94:95]
	ds_read_b128 v[2:5], v199 offset:50176
	v_pk_fma_f32 v[88:89], v[46:47], v[96:97], v[88:89]
	ds_read_b128 v[6:9], v199 offset:50192
	v_pk_fma_f32 v[88:89], v[48:49], v[98:99], v[88:89]
	ds_read_b128 v[34:37], v199 offset:51200
	v_pk_fma_f32 v[88:89], v[50:51], v[100:101], v[88:89]
	ds_read_b128 v[38:41], v199 offset:51216
	v_add_f32_e32 v86, v88, v89
	ds_read_b32 v42, v200 offset:50176
	ds_read_b128 v[18:21], v199 offset:49120
	ds_read_b128 v[22:25], v199 offset:49136
	v_add_f32_dpp v86, v86, v86 quad_perm:[1,0,3,2] row_mask:0xf bank_mask:0xf bound_ctrl:1
	v_add_f32_dpp v93, v93, v93 quad_perm:[1,0,3,2] row_mask:0xf bank_mask:0xf bound_ctrl:1
	ds_read_b128 v[26:29], v199 offset:50944
	v_add_f32_dpp v86, v86, v86 quad_perm:[2,3,0,1] row_mask:0xf bank_mask:0xf bound_ctrl:1
	v_add_f32_dpp v93, v93, v93 quad_perm:[2,3,0,1] row_mask:0xf bank_mask:0xf bound_ctrl:1
	ds_read_b128 v[30:33], v199 offset:50960
	v_add_f32_dpp v86, v86, v86 row_half_mirror row_mask:0xf bank_mask:0xf bound_ctrl:1
	v_add_f32_dpp v93, v93, v93 row_half_mirror row_mask:0xf bank_mask:0xf bound_ctrl:1
	v_pk_fma_f32 v[162:163], v[76:77], v[84:85], v[94:95] op_sel_hi:[1,0,1]
	v_pk_fma_f32 v[164:165], v[78:79], v[84:85], v[96:97] op_sel_hi:[1,0,1]
	v_pk_fma_f32 v[166:167], v[80:81], v[84:85], v[98:99] op_sel_hi:[1,0,1]
	v_pk_fma_f32 v[168:169], v[82:83], v[84:85], v[100:101] op_sel_hi:[1,0,1]
	s_waitcnt lgkmcnt(12)
	v_pk_fma_f32 v[170:171], v[68:69], v[86:87], v[162:163] op_sel_hi:[1,0,1]
	v_pk_fma_f32 v[172:173], v[70:71], v[86:87], v[164:165] op_sel_hi:[1,0,1]
	v_pk_fma_f32 v[174:175], v[72:73], v[86:87], v[166:167] op_sel_hi:[1,0,1]
	v_pk_fma_f32 v[176:177], v[74:75], v[86:87], v[168:169] op_sel_hi:[1,0,1]
	s_waitcnt lgkmcnt(2)
	v_pk_mul_f32 v[170:171], v[170:171], v[18:19]
	v_pk_mul_f32 v[172:173], v[172:173], v[20:21]
	v_pk_mul_f32 v[174:175], v[174:175], v[22:23]
	v_pk_mul_f32 v[176:177], v[176:177], v[24:25]
	ds_write_b32 v201, v93 offset:7424
	v_pk_mul_f32 v[90:91], v[10:11], v[94:95]
	v_pk_fma_f32 v[90:91], v[12:13], v[96:97], v[90:91]
	v_pk_fma_f32 v[90:91], v[14:15], v[98:99], v[90:91]
	v_pk_fma_f32 v[90:91], v[16:17], v[100:101], v[90:91]
	ds_read_b128 v[10:13], v199 offset:50432
	v_add_f32_e32 v92, v90, v91
	ds_read_b128 v[14:17], v199 offset:50448
	v_pk_mul_f32 v[90:91], v[52:53], v[170:171]
	v_add_f32_dpp v92, v92, v92 quad_perm:[1,0,3,2] row_mask:0xf bank_mask:0xf bound_ctrl:1
	v_pk_fma_f32 v[90:91], v[54:55], v[172:173], v[90:91]
	v_pk_fma_f32 v[90:91], v[56:57], v[174:175], v[90:91]
	v_add_f32_dpp v92, v92, v92 quad_perm:[2,3,0,1] row_mask:0xf bank_mask:0xf bound_ctrl:1
	v_pk_fma_f32 v[90:91], v[58:59], v[176:177], v[90:91]
	v_add_f32_e32 v93, v90, v91
	v_add_f32_dpp v92, v92, v92 row_half_mirror row_mask:0xf bank_mask:0xf bound_ctrl:1
	s_nop 0
	v_add_f32_dpp v93, v93, v93 quad_perm:[1,0,3,2] row_mask:0xf bank_mask:0xf bound_ctrl:1
	ds_write_b32 v201, v92 offset:7680
	s_nop 0
	v_add_f32_dpp v93, v93, v93 quad_perm:[2,3,0,1] row_mask:0xf bank_mask:0xf bound_ctrl:1
	s_nop 1
	v_add_f32_dpp v93, v93, v93 row_half_mirror row_mask:0xf bank_mask:0xf bound_ctrl:1
	s_nop 0
	ds_write_b32 v201, v93 offset:7936
